# GEMM_out epilogue: all residual loads issued up front + DPP row sums; final RMSNorm: gains hoisted, rows prefetched
# speedup vs baseline: 1.0154x; 1.0154x over previous
; DI unsigned pack2(float a, float b) { f32x2 v = {a, b}; bf16x2_t r = __builtin_convertvector(v, bf16x2_t); return __builtin_bit_cast(unsigned, r); }
; DI float bflo(unsigned v) { return __uint_as_float(v << 16); }
; DI float bfhi(unsigned v) { return __uint_as_float(v & 0xffff0000u); }
; DI size_t blk(size_t row, int k, int R) { return ((size_t)(k >> 5) * R + row) * 32 + (k & 31); }
; DI void gemm_tile(const Params& p, const GemmJob& j, int mt, int nt, char* smem) {
;     ...
; #pragma unroll 4
;     for (int q = 0; q < 16; ++q) {
;       const int idx = tid + 256 * q, row = idx >> 4, col = (idx & 15) * 8;
;       const u32x4 av = *(const u32x4*)(Cs + row * 136 + col);
;       bf16_t* xq = j.xbp + blk(t0 + row, n0 + col, NTOK);
;       float rv[8];
;       if (j.res) {
;         const f32x4 r0 = *(const f32x4*)(j.res + (size_t)(t0 + row) * 1024 + n0 + col), r1 = *(const f32x4*)(j.res + (size_t)(t0 + row) * 1024 + n0 + col + 4);
;         rv[0] = r0[0]; rv[1] = r0[1]; rv[2] = r0[2]; rv[3] = r0[3]; rv[4] = r1[0]; rv[5] = r1[1]; rv[6] = r1[2]; rv[7] = r1[3];
;       } else {
;         const u32x4 rb = *(const u32x4*)xq;
; #pragma unroll
;         for (int e = 0; e < 4; ++e) { rv[2 * e] = bflo(rb[e]); rv[2 * e + 1] = bfhi(rb[e]); }
;       }
;       float o[8]; float ss = 0.f;
; #pragma unroll
;       for (int e = 0; e < 4; ++e) { o[2 * e] = rv[2 * e] + bflo(av[e]); o[2 * e + 1] = rv[2 * e + 1] + bfhi(av[e]); ss += o[2 * e] * o[2 * e] + o[2 * e + 1] * o[2 * e + 1]; }
;       *(u32x4*)xq = (u32x4){pack2(o[0], o[1]), pack2(o[2], o[3]), pack2(o[4], o[5]), pack2(o[6], o[7])};
.Lepi_out_start:
	v_lshrrev_b32_e32 v0, 4, v134
	v_add_u32_e32 v20, s28, v0
	v_ashrrev_i32_e32 v21, 31, v20
	v_mad_u32_u24 v2, v0, s0, v14
	v_lshlrev_b64 v[22:23], 6, v[20:21]
	v_lshl_add_u64 v[22:23], v[16:17], 0, v[22:23]
	s_mov_b64 s[6:7], 0x1000
	v_lshl_add_u64 v[22:23], v[22:23], 0, s[6:7]
	s_mov_b64 s[30:31], 0x2000
	v_lshl_add_u64 v[158:159], v[22:23], 0, s[30:31]
	s_andn2_b64 vcc, exec, s[8:9]
	s_cbranch_vccz .Lepi_out_res
	global_load_dwordx4 v[32:35], v[22:23], off offset:-4096
	global_load_dwordx4 v[36:39], v[22:23], off offset:-3072
	global_load_dwordx4 v[40:43], v[22:23], off offset:-2048
	global_load_dwordx4 v[44:47], v[22:23], off offset:-1024
	global_load_dwordx4 v[48:51], v[22:23], off
	global_load_dwordx4 v[52:55], v[22:23], off offset:1024
	global_load_dwordx4 v[56:59], v[22:23], off offset:2048
	global_load_dwordx4 v[60:63], v[22:23], off offset:3072
	global_load_dwordx4 v[64:67], v[158:159], off offset:-4096
	global_load_dwordx4 v[68:71], v[158:159], off offset:-3072
	global_load_dwordx4 v[72:75], v[158:159], off offset:-2048
	global_load_dwordx4 v[76:79], v[158:159], off offset:-1024
	global_load_dwordx4 v[80:83], v[158:159], off
	global_load_dwordx4 v[84:87], v[158:159], off offset:1024
	global_load_dwordx4 v[88:91], v[158:159], off offset:2048
	global_load_dwordx4 v[92:95], v[158:159], off offset:3072
	ds_read_b128 v[96:99], v2
	ds_read_b128 v[100:103], v2 offset:4352
	ds_read_b128 v[104:107], v2 offset:8704
	ds_read_b128 v[108:111], v2 offset:13056
	ds_read_b128 v[112:115], v2 offset:17408
	ds_read_b128 v[116:119], v2 offset:21760
	ds_read_b128 v[120:123], v2 offset:26112
	ds_read_b128 v[124:127], v2 offset:30464
	s_waitcnt vmcnt(15) lgkmcnt(7)
	v_lshlrev_b32_e32 v12, 16, v32
	v_and_b32_e32 v13, 0xffff0000, v32
	v_lshlrev_b32_e32 v28, 16, v33
	v_and_b32_e32 v29, 0xffff0000, v33
	v_lshlrev_b32_e32 v30, 16, v34
	v_and_b32_e32 v31, 0xffff0000, v34
	v_lshlrev_b32_e32 v128, 16, v35
	v_and_b32_e32 v129, 0xffff0000, v35
	v_lshlrev_b32_e32 v4, 16, v96
	v_and_b32_e32 v5, 0xffff0000, v96
	v_lshlrev_b32_e32 v6, 16, v97
	v_and_b32_e32 v7, 0xffff0000, v97
	v_lshlrev_b32_e32 v8, 16, v98
	v_and_b32_e32 v9, 0xffff0000, v98
	v_lshlrev_b32_e32 v10, 16, v99
	v_and_b32_e32 v11, 0xffff0000, v99
	v_add_f32_e32 v12, v12, v4
	v_add_f32_e32 v13, v13, v5
	v_add_f32_e32 v28, v28, v6
	v_add_f32_e32 v29, v29, v7
	v_add_f32_e32 v30, v30, v8
	v_add_f32_e32 v31, v31, v9
	v_add_f32_e32 v128, v128, v10
	v_add_f32_e32 v129, v129, v11
	v_mul_f32_e32 v142, v12, v12
	v_fmac_f32_e32 v142, v13, v13
	v_fmac_f32_e32 v142, v28, v28
	v_fmac_f32_e32 v142, v29, v29
	v_fmac_f32_e32 v142, v30, v30
	v_fmac_f32_e32 v142, v31, v31
	v_fmac_f32_e32 v142, v128, v128
	v_fmac_f32_e32 v142, v129, v129
	v_cvt_pk_bf16_f32 v32, v12, v13
	v_cvt_pk_bf16_f32 v33, v28, v29
	v_cvt_pk_bf16_f32 v34, v30, v31
	v_cvt_pk_bf16_f32 v35, v128, v129
	global_store_dwordx4 v[22:23], v[32:35], off offset:-4096
	s_waitcnt vmcnt(15) lgkmcnt(6)
	v_lshlrev_b32_e32 v12, 16, v36
	v_and_b32_e32 v13, 0xffff0000, v36
	v_lshlrev_b32_e32 v28, 16, v37
	v_and_b32_e32 v29, 0xffff0000, v37
	v_lshlrev_b32_e32 v30, 16, v38
	v_and_b32_e32 v31, 0xffff0000, v38
	v_lshlrev_b32_e32 v128, 16, v39
	v_and_b32_e32 v129, 0xffff0000, v39
	v_lshlrev_b32_e32 v4, 16, v100
	v_and_b32_e32 v5, 0xffff0000, v100
	v_lshlrev_b32_e32 v6, 16, v101
	v_and_b32_e32 v7, 0xffff0000, v101
	v_lshlrev_b32_e32 v8, 16, v102
	v_and_b32_e32 v9, 0xffff0000, v102
	v_lshlrev_b32_e32 v10, 16, v103
	v_and_b32_e32 v11, 0xffff0000, v103
	v_add_f32_e32 v12, v12, v4
	v_add_f32_e32 v13, v13, v5
	v_add_f32_e32 v28, v28, v6
	v_add_f32_e32 v29, v29, v7
	v_add_f32_e32 v30, v30, v8
	v_add_f32_e32 v31, v31, v9
	v_add_f32_e32 v128, v128, v10
	v_add_f32_e32 v129, v129, v11
	v_mul_f32_e32 v143, v12, v12
	v_fmac_f32_e32 v143, v13, v13
	v_fmac_f32_e32 v143, v28, v28
	v_fmac_f32_e32 v143, v29, v29
	v_fmac_f32_e32 v143, v30, v30
	v_fmac_f32_e32 v143, v31, v31
	v_fmac_f32_e32 v143, v128, v128
	v_fmac_f32_e32 v143, v129, v129
	v_cvt_pk_bf16_f32 v36, v12, v13
	v_cvt_pk_bf16_f32 v37, v28, v29
	v_cvt_pk_bf16_f32 v38, v30, v31
	v_cvt_pk_bf16_f32 v39, v128, v129
	global_store_dwordx4 v[22:23], v[36:39], off offset:-3072
	s_waitcnt vmcnt(15) lgkmcnt(5)
	v_lshlrev_b32_e32 v12, 16, v40
	v_and_b32_e32 v13, 0xffff0000, v40
	v_lshlrev_b32_e32 v28, 16, v41
	v_and_b32_e32 v29, 0xffff0000, v41
	v_lshlrev_b32_e32 v30, 16, v42
	v_and_b32_e32 v31, 0xffff0000, v42
	v_lshlrev_b32_e32 v128, 16, v43
	v_and_b32_e32 v129, 0xffff0000, v43
	v_lshlrev_b32_e32 v4, 16, v104
	v_and_b32_e32 v5, 0xffff0000, v104
	v_lshlrev_b32_e32 v6, 16, v105
	v_and_b32_e32 v7, 0xffff0000, v105
	v_lshlrev_b32_e32 v8, 16, v106
	v_and_b32_e32 v9, 0xffff0000, v106
	v_lshlrev_b32_e32 v10, 16, v107
	v_and_b32_e32 v11, 0xffff0000, v107
	v_add_f32_e32 v12, v12, v4
	v_add_f32_e32 v13, v13, v5
	v_add_f32_e32 v28, v28, v6
	v_add_f32_e32 v29, v29, v7
	v_add_f32_e32 v30, v30, v8
	v_add_f32_e32 v31, v31, v9
	v_add_f32_e32 v128, v128, v10
	v_add_f32_e32 v129, v129, v11
	v_mul_f32_e32 v144, v12, v12
	v_fmac_f32_e32 v144, v13, v13
	v_fmac_f32_e32 v144, v28, v28
	v_fmac_f32_e32 v144, v29, v29
	v_fmac_f32_e32 v144, v30, v30
	v_fmac_f32_e32 v144, v31, v31
	v_fmac_f32_e32 v144, v128, v128
	v_fmac_f32_e32 v144, v129, v129
	v_cvt_pk_bf16_f32 v40, v12, v13
	v_cvt_pk_bf16_f32 v41, v28, v29
	v_cvt_pk_bf16_f32 v42, v30, v31
	v_cvt_pk_bf16_f32 v43, v128, v129
	global_store_dwordx4 v[22:23], v[40:43], off offset:-2048
	s_waitcnt vmcnt(15) lgkmcnt(4)
; DI unsigned pack2(float a, float b) { f32x2 v = {a, b}; bf16x2_t r = __builtin_convertvector(v, bf16x2_t); return __builtin_bit_cast(unsigned, r); }
; DI float bflo(unsigned v) { return __uint_as_float(v << 16); }
; DI float bfhi(unsigned v) { return __uint_as_float(v & 0xffff0000u); }
; DI size_t blk(size_t row, int k, int R) { return ((size_t)(k >> 5) * R + row) * 32 + (k & 31); }
; DI void gemm_tile(const Params& p, const GemmJob& j, int mt, int nt, char* smem) {
;     ...
;     for (int q = 0; q < 16; ++q) {
;       const int idx = tid + 256 * q, row = idx >> 4, col = (idx & 15) * 8;
;       const u32x4 av = *(const u32x4*)(Cs + row * 136 + col);
;       bf16_t* xq = j.xbp + blk(t0 + row, n0 + col, NTOK);
;       float rv[8];
;       if (j.res) {
;         const f32x4 r0 = *(const f32x4*)(j.res + (size_t)(t0 + row) * 1024 + n0 + col), r1 = *(const f32x4*)(j.res + (size_t)(t0 + row) * 1024 + n0 + col + 4);
;         rv[0] = r0[0]; rv[1] = r0[1]; rv[2] = r0[2]; rv[3] = r0[3]; rv[4] = r1[0]; rv[5] = r1[1]; rv[6] = r1[2]; rv[7] = r1[3];
;       } else {
;         const u32x4 rb = *(const u32x4*)xq;
; #pragma unroll
;         for (int e = 0; e < 4; ++e) { rv[2 * e] = bflo(rb[e]); rv[2 * e + 1] = bfhi(rb[e]); }
;       }
;       float o[8]; float ss = 0.f;
; #pragma unroll
;       for (int e = 0; e < 4; ++e) { o[2 * e] = rv[2 * e] + bflo(av[e]); o[2 * e + 1] = rv[2 * e + 1] + bfhi(av[e]); ss += o[2 * e] * o[2 * e] + o[2 * e + 1] * o[2 * e + 1]; }
;       *(u32x4*)xq = (u32x4){pack2(o[0], o[1]), pack2(o[2], o[3]), pack2(o[4], o[5]), pack2(o[6], o[7])};
	v_lshlrev_b32_e32 v12, 16, v44
	v_and_b32_e32 v13, 0xffff0000, v44
	v_lshlrev_b32_e32 v28, 16, v45
	v_and_b32_e32 v29, 0xffff0000, v45
	v_lshlrev_b32_e32 v30, 16, v46
	v_and_b32_e32 v31, 0xffff0000, v46
	v_lshlrev_b32_e32 v128, 16, v47
	v_and_b32_e32 v129, 0xffff0000, v47
	v_lshlrev_b32_e32 v4, 16, v108
	v_and_b32_e32 v5, 0xffff0000, v108
	v_lshlrev_b32_e32 v6, 16, v109
	v_and_b32_e32 v7, 0xffff0000, v109
	v_lshlrev_b32_e32 v8, 16, v110
	v_and_b32_e32 v9, 0xffff0000, v110
	v_lshlrev_b32_e32 v10, 16, v111
	v_and_b32_e32 v11, 0xffff0000, v111
	v_add_f32_e32 v12, v12, v4
	v_add_f32_e32 v13, v13, v5
	v_add_f32_e32 v28, v28, v6
	v_add_f32_e32 v29, v29, v7
	v_add_f32_e32 v30, v30, v8
	v_add_f32_e32 v31, v31, v9
	v_add_f32_e32 v128, v128, v10
	v_add_f32_e32 v129, v129, v11
	v_mul_f32_e32 v145, v12, v12
	v_fmac_f32_e32 v145, v13, v13
	v_fmac_f32_e32 v145, v28, v28
	v_fmac_f32_e32 v145, v29, v29
	v_fmac_f32_e32 v145, v30, v30
	v_fmac_f32_e32 v145, v31, v31
	v_fmac_f32_e32 v145, v128, v128
	v_fmac_f32_e32 v145, v129, v129
	v_cvt_pk_bf16_f32 v44, v12, v13
	v_cvt_pk_bf16_f32 v45, v28, v29
	v_cvt_pk_bf16_f32 v46, v30, v31
	v_cvt_pk_bf16_f32 v47, v128, v129
	global_store_dwordx4 v[22:23], v[44:47], off offset:-1024
	s_waitcnt vmcnt(15) lgkmcnt(3)
	v_lshlrev_b32_e32 v12, 16, v48
	v_and_b32_e32 v13, 0xffff0000, v48
	v_lshlrev_b32_e32 v28, 16, v49
	v_and_b32_e32 v29, 0xffff0000, v49
	v_lshlrev_b32_e32 v30, 16, v50
	v_and_b32_e32 v31, 0xffff0000, v50
	v_lshlrev_b32_e32 v128, 16, v51
	v_and_b32_e32 v129, 0xffff0000, v51
	v_lshlrev_b32_e32 v4, 16, v112
	v_and_b32_e32 v5, 0xffff0000, v112
	v_lshlrev_b32_e32 v6, 16, v113
	v_and_b32_e32 v7, 0xffff0000, v113
	v_lshlrev_b32_e32 v8, 16, v114
	v_and_b32_e32 v9, 0xffff0000, v114
	v_lshlrev_b32_e32 v10, 16, v115
	v_and_b32_e32 v11, 0xffff0000, v115
	v_add_f32_e32 v12, v12, v4
	v_add_f32_e32 v13, v13, v5
	v_add_f32_e32 v28, v28, v6
	v_add_f32_e32 v29, v29, v7
	v_add_f32_e32 v30, v30, v8
	v_add_f32_e32 v31, v31, v9
	v_add_f32_e32 v128, v128, v10
	v_add_f32_e32 v129, v129, v11
	v_mul_f32_e32 v146, v12, v12
	v_fmac_f32_e32 v146, v13, v13
	v_fmac_f32_e32 v146, v28, v28
	v_fmac_f32_e32 v146, v29, v29
	v_fmac_f32_e32 v146, v30, v30
	v_fmac_f32_e32 v146, v31, v31
	v_fmac_f32_e32 v146, v128, v128
	v_fmac_f32_e32 v146, v129, v129
	v_cvt_pk_bf16_f32 v48, v12, v13
	v_cvt_pk_bf16_f32 v49, v28, v29
	v_cvt_pk_bf16_f32 v50, v30, v31
	v_cvt_pk_bf16_f32 v51, v128, v129
	global_store_dwordx4 v[22:23], v[48:51], off
	s_waitcnt vmcnt(15) lgkmcnt(2)
	v_lshlrev_b32_e32 v12, 16, v52
	v_and_b32_e32 v13, 0xffff0000, v52
	v_lshlrev_b32_e32 v28, 16, v53
	v_and_b32_e32 v29, 0xffff0000, v53
	v_lshlrev_b32_e32 v30, 16, v54
	v_and_b32_e32 v31, 0xffff0000, v54
	v_lshlrev_b32_e32 v128, 16, v55
	v_and_b32_e32 v129, 0xffff0000, v55
	v_lshlrev_b32_e32 v4, 16, v116
	v_and_b32_e32 v5, 0xffff0000, v116
	v_lshlrev_b32_e32 v6, 16, v117
	v_and_b32_e32 v7, 0xffff0000, v117
	v_lshlrev_b32_e32 v8, 16, v118
	v_and_b32_e32 v9, 0xffff0000, v118
	v_lshlrev_b32_e32 v10, 16, v119
	v_and_b32_e32 v11, 0xffff0000, v119
	v_add_f32_e32 v12, v12, v4
	v_add_f32_e32 v13, v13, v5
	v_add_f32_e32 v28, v28, v6
	v_add_f32_e32 v29, v29, v7
	v_add_f32_e32 v30, v30, v8
	v_add_f32_e32 v31, v31, v9
	v_add_f32_e32 v128, v128, v10
	v_add_f32_e32 v129, v129, v11
	v_mul_f32_e32 v147, v12, v12
	v_fmac_f32_e32 v147, v13, v13
	v_fmac_f32_e32 v147, v28, v28
	v_fmac_f32_e32 v147, v29, v29
	v_fmac_f32_e32 v147, v30, v30
	v_fmac_f32_e32 v147, v31, v31
	v_fmac_f32_e32 v147, v128, v128
	v_fmac_f32_e32 v147, v129, v129
	v_cvt_pk_bf16_f32 v52, v12, v13
	v_cvt_pk_bf16_f32 v53, v28, v29
	v_cvt_pk_bf16_f32 v54, v30, v31
	v_cvt_pk_bf16_f32 v55, v128, v129
	global_store_dwordx4 v[22:23], v[52:55], off offset:1024
	s_waitcnt vmcnt(15) lgkmcnt(1)
	v_lshlrev_b32_e32 v12, 16, v56
	v_and_b32_e32 v13, 0xffff0000, v56
	v_lshlrev_b32_e32 v28, 16, v57
	v_and_b32_e32 v29, 0xffff0000, v57
	v_lshlrev_b32_e32 v30, 16, v58
	v_and_b32_e32 v31, 0xffff0000, v58
	v_lshlrev_b32_e32 v128, 16, v59
	v_and_b32_e32 v129, 0xffff0000, v59
	v_lshlrev_b32_e32 v4, 16, v120
	v_and_b32_e32 v5, 0xffff0000, v120
	v_lshlrev_b32_e32 v6, 16, v121
	v_and_b32_e32 v7, 0xffff0000, v121
	v_lshlrev_b32_e32 v8, 16, v122
	v_and_b32_e32 v9, 0xffff0000, v122
	v_lshlrev_b32_e32 v10, 16, v123
	v_and_b32_e32 v11, 0xffff0000, v123
	v_add_f32_e32 v12, v12, v4
	v_add_f32_e32 v13, v13, v5
	v_add_f32_e32 v28, v28, v6
	v_add_f32_e32 v29, v29, v7
	v_add_f32_e32 v30, v30, v8
	v_add_f32_e32 v31, v31, v9
	v_add_f32_e32 v128, v128, v10
	v_add_f32_e32 v129, v129, v11
	v_mul_f32_e32 v148, v12, v12
	v_fmac_f32_e32 v148, v13, v13
	v_fmac_f32_e32 v148, v28, v28
	v_fmac_f32_e32 v148, v29, v29
	v_fmac_f32_e32 v148, v30, v30
	v_fmac_f32_e32 v148, v31, v31
	v_fmac_f32_e32 v148, v128, v128
	v_fmac_f32_e32 v148, v129, v129
	v_cvt_pk_bf16_f32 v56, v12, v13
	v_cvt_pk_bf16_f32 v57, v28, v29
	v_cvt_pk_bf16_f32 v58, v30, v31
	v_cvt_pk_bf16_f32 v59, v128, v129
	global_store_dwordx4 v[22:23], v[56:59], off offset:2048
	s_waitcnt vmcnt(15) lgkmcnt(0)
; DI unsigned pack2(float a, float b) { f32x2 v = {a, b}; bf16x2_t r = __builtin_convertvector(v, bf16x2_t); return __builtin_bit_cast(unsigned, r); }
; DI float bflo(unsigned v) { return __uint_as_float(v << 16); }
; DI float bfhi(unsigned v) { return __uint_as_float(v & 0xffff0000u); }
; DI size_t blk(size_t row, int k, int R) { return ((size_t)(k >> 5) * R + row) * 32 + (k & 31); }
; DI void gemm_tile(const Params& p, const GemmJob& j, int mt, int nt, char* smem) {
;     ...
;     for (int q = 0; q < 16; ++q) {
;       const int idx = tid + 256 * q, row = idx >> 4, col = (idx & 15) * 8;
;       const u32x4 av = *(const u32x4*)(Cs + row * 136 + col);
;       bf16_t* xq = j.xbp + blk(t0 + row, n0 + col, NTOK);
;       float rv[8];
;       if (j.res) {
;         const f32x4 r0 = *(const f32x4*)(j.res + (size_t)(t0 + row) * 1024 + n0 + col), r1 = *(const f32x4*)(j.res + (size_t)(t0 + row) * 1024 + n0 + col + 4);
;         rv[0] = r0[0]; rv[1] = r0[1]; rv[2] = r0[2]; rv[3] = r0[3]; rv[4] = r1[0]; rv[5] = r1[1]; rv[6] = r1[2]; rv[7] = r1[3];
;       } else {
;         const u32x4 rb = *(const u32x4*)xq;
; #pragma unroll
;         for (int e = 0; e < 4; ++e) { rv[2 * e] = bflo(rb[e]); rv[2 * e + 1] = bfhi(rb[e]); }
;       }
;       float o[8]; float ss = 0.f;
; #pragma unroll
;       for (int e = 0; e < 4; ++e) { o[2 * e] = rv[2 * e] + bflo(av[e]); o[2 * e + 1] = rv[2 * e + 1] + bfhi(av[e]); ss += o[2 * e] * o[2 * e] + o[2 * e + 1] * o[2 * e + 1]; }
;       *(u32x4*)xq = (u32x4){pack2(o[0], o[1]), pack2(o[2], o[3]), pack2(o[4], o[5]), pack2(o[6], o[7])};
	v_lshlrev_b32_e32 v12, 16, v60
	v_and_b32_e32 v13, 0xffff0000, v60
	v_lshlrev_b32_e32 v28, 16, v61
	v_and_b32_e32 v29, 0xffff0000, v61
	v_lshlrev_b32_e32 v30, 16, v62
	v_and_b32_e32 v31, 0xffff0000, v62
	v_lshlrev_b32_e32 v128, 16, v63
	v_and_b32_e32 v129, 0xffff0000, v63
	v_lshlrev_b32_e32 v4, 16, v124
	v_and_b32_e32 v5, 0xffff0000, v124
	v_lshlrev_b32_e32 v6, 16, v125
	v_and_b32_e32 v7, 0xffff0000, v125
	v_lshlrev_b32_e32 v8, 16, v126
	v_and_b32_e32 v9, 0xffff0000, v126
	v_lshlrev_b32_e32 v10, 16, v127
	v_and_b32_e32 v11, 0xffff0000, v127
	v_add_f32_e32 v12, v12, v4
	v_add_f32_e32 v13, v13, v5
	v_add_f32_e32 v28, v28, v6
	v_add_f32_e32 v29, v29, v7
	v_add_f32_e32 v30, v30, v8
	v_add_f32_e32 v31, v31, v9
	v_add_f32_e32 v128, v128, v10
	v_add_f32_e32 v129, v129, v11
	v_mul_f32_e32 v149, v12, v12
	v_fmac_f32_e32 v149, v13, v13
	v_fmac_f32_e32 v149, v28, v28
	v_fmac_f32_e32 v149, v29, v29
	v_fmac_f32_e32 v149, v30, v30
	v_fmac_f32_e32 v149, v31, v31
	v_fmac_f32_e32 v149, v128, v128
	v_fmac_f32_e32 v149, v129, v129
	v_cvt_pk_bf16_f32 v60, v12, v13
	v_cvt_pk_bf16_f32 v61, v28, v29
	v_cvt_pk_bf16_f32 v62, v30, v31
	v_cvt_pk_bf16_f32 v63, v128, v129
	global_store_dwordx4 v[22:23], v[60:63], off offset:3072
	ds_read_b128 v[96:99], v2 offset:34816
	ds_read_b128 v[100:103], v2 offset:39168
	ds_read_b128 v[104:107], v2 offset:43520
	ds_read_b128 v[108:111], v2 offset:47872
	ds_read_b128 v[112:115], v2 offset:52224
	ds_read_b128 v[116:119], v2 offset:56576
	ds_read_b128 v[120:123], v2 offset:60928
	ds_read_b128 v[124:127], v2 offset:65280
	s_waitcnt vmcnt(15) lgkmcnt(7)
	v_lshlrev_b32_e32 v12, 16, v64
	v_and_b32_e32 v13, 0xffff0000, v64
	v_lshlrev_b32_e32 v28, 16, v65
	v_and_b32_e32 v29, 0xffff0000, v65
	v_lshlrev_b32_e32 v30, 16, v66
	v_and_b32_e32 v31, 0xffff0000, v66
	v_lshlrev_b32_e32 v128, 16, v67
	v_and_b32_e32 v129, 0xffff0000, v67
	v_lshlrev_b32_e32 v4, 16, v96
	v_and_b32_e32 v5, 0xffff0000, v96
	v_lshlrev_b32_e32 v6, 16, v97
	v_and_b32_e32 v7, 0xffff0000, v97
	v_lshlrev_b32_e32 v8, 16, v98
	v_and_b32_e32 v9, 0xffff0000, v98
	v_lshlrev_b32_e32 v10, 16, v99
	v_and_b32_e32 v11, 0xffff0000, v99
	v_add_f32_e32 v12, v12, v4
	v_add_f32_e32 v13, v13, v5
	v_add_f32_e32 v28, v28, v6
	v_add_f32_e32 v29, v29, v7
	v_add_f32_e32 v30, v30, v8
	v_add_f32_e32 v31, v31, v9
	v_add_f32_e32 v128, v128, v10
	v_add_f32_e32 v129, v129, v11
	v_mul_f32_e32 v150, v12, v12
	v_fmac_f32_e32 v150, v13, v13
	v_fmac_f32_e32 v150, v28, v28
	v_fmac_f32_e32 v150, v29, v29
	v_fmac_f32_e32 v150, v30, v30
	v_fmac_f32_e32 v150, v31, v31
	v_fmac_f32_e32 v150, v128, v128
	v_fmac_f32_e32 v150, v129, v129
	v_cvt_pk_bf16_f32 v64, v12, v13
	v_cvt_pk_bf16_f32 v65, v28, v29
	v_cvt_pk_bf16_f32 v66, v30, v31
	v_cvt_pk_bf16_f32 v67, v128, v129
	global_store_dwordx4 v[158:159], v[64:67], off offset:-4096
	s_waitcnt vmcnt(15) lgkmcnt(6)
	v_lshlrev_b32_e32 v12, 16, v68
	v_and_b32_e32 v13, 0xffff0000, v68
	v_lshlrev_b32_e32 v28, 16, v69
	v_and_b32_e32 v29, 0xffff0000, v69
	v_lshlrev_b32_e32 v30, 16, v70
	v_and_b32_e32 v31, 0xffff0000, v70
	v_lshlrev_b32_e32 v128, 16, v71
	v_and_b32_e32 v129, 0xffff0000, v71
	v_lshlrev_b32_e32 v4, 16, v100
	v_and_b32_e32 v5, 0xffff0000, v100
	v_lshlrev_b32_e32 v6, 16, v101
	v_and_b32_e32 v7, 0xffff0000, v101
	v_lshlrev_b32_e32 v8, 16, v102
	v_and_b32_e32 v9, 0xffff0000, v102
	v_lshlrev_b32_e32 v10, 16, v103
	v_and_b32_e32 v11, 0xffff0000, v103
	v_add_f32_e32 v12, v12, v4
	v_add_f32_e32 v13, v13, v5
	v_add_f32_e32 v28, v28, v6
	v_add_f32_e32 v29, v29, v7
	v_add_f32_e32 v30, v30, v8
	v_add_f32_e32 v31, v31, v9
	v_add_f32_e32 v128, v128, v10
	v_add_f32_e32 v129, v129, v11
	v_mul_f32_e32 v151, v12, v12
	v_fmac_f32_e32 v151, v13, v13
	v_fmac_f32_e32 v151, v28, v28
	v_fmac_f32_e32 v151, v29, v29
	v_fmac_f32_e32 v151, v30, v30
	v_fmac_f32_e32 v151, v31, v31
	v_fmac_f32_e32 v151, v128, v128
	v_fmac_f32_e32 v151, v129, v129
	v_cvt_pk_bf16_f32 v68, v12, v13
	v_cvt_pk_bf16_f32 v69, v28, v29
	v_cvt_pk_bf16_f32 v70, v30, v31
	v_cvt_pk_bf16_f32 v71, v128, v129
	global_store_dwordx4 v[158:159], v[68:71], off offset:-3072
	s_waitcnt vmcnt(15) lgkmcnt(5)
	v_lshlrev_b32_e32 v12, 16, v72
	v_and_b32_e32 v13, 0xffff0000, v72
	v_lshlrev_b32_e32 v28, 16, v73
	v_and_b32_e32 v29, 0xffff0000, v73
	v_lshlrev_b32_e32 v30, 16, v74
	v_and_b32_e32 v31, 0xffff0000, v74
	v_lshlrev_b32_e32 v128, 16, v75
	v_and_b32_e32 v129, 0xffff0000, v75
	v_lshlrev_b32_e32 v4, 16, v104
	v_and_b32_e32 v5, 0xffff0000, v104
	v_lshlrev_b32_e32 v6, 16, v105
	v_and_b32_e32 v7, 0xffff0000, v105
	v_lshlrev_b32_e32 v8, 16, v106
	v_and_b32_e32 v9, 0xffff0000, v106
	v_lshlrev_b32_e32 v10, 16, v107
	v_and_b32_e32 v11, 0xffff0000, v107
	v_add_f32_e32 v12, v12, v4
	v_add_f32_e32 v13, v13, v5
	v_add_f32_e32 v28, v28, v6
	v_add_f32_e32 v29, v29, v7
	v_add_f32_e32 v30, v30, v8
	v_add_f32_e32 v31, v31, v9
	v_add_f32_e32 v128, v128, v10
	v_add_f32_e32 v129, v129, v11
	v_mul_f32_e32 v152, v12, v12
	v_fmac_f32_e32 v152, v13, v13
	v_fmac_f32_e32 v152, v28, v28
	v_fmac_f32_e32 v152, v29, v29
	v_fmac_f32_e32 v152, v30, v30
	v_fmac_f32_e32 v152, v31, v31
	v_fmac_f32_e32 v152, v128, v128
	v_fmac_f32_e32 v152, v129, v129
	v_cvt_pk_bf16_f32 v72, v12, v13
	v_cvt_pk_bf16_f32 v73, v28, v29
	v_cvt_pk_bf16_f32 v74, v30, v31
	v_cvt_pk_bf16_f32 v75, v128, v129
	global_store_dwordx4 v[158:159], v[72:75], off offset:-2048
	s_waitcnt vmcnt(15) lgkmcnt(4)
; DI unsigned pack2(float a, float b) { f32x2 v = {a, b}; bf16x2_t r = __builtin_convertvector(v, bf16x2_t); return __builtin_bit_cast(unsigned, r); }
; DI float bflo(unsigned v) { return __uint_as_float(v << 16); }
; DI float bfhi(unsigned v) { return __uint_as_float(v & 0xffff0000u); }
; DI size_t blk(size_t row, int k, int R) { return ((size_t)(k >> 5) * R + row) * 32 + (k & 31); }
; DI void gemm_tile(const Params& p, const GemmJob& j, int mt, int nt, char* smem) {
;     ...
;     for (int q = 0; q < 16; ++q) {
;       const int idx = tid + 256 * q, row = idx >> 4, col = (idx & 15) * 8;
;       const u32x4 av = *(const u32x4*)(Cs + row * 136 + col);
;       bf16_t* xq = j.xbp + blk(t0 + row, n0 + col, NTOK);
;       float rv[8];
;       if (j.res) {
;         const f32x4 r0 = *(const f32x4*)(j.res + (size_t)(t0 + row) * 1024 + n0 + col), r1 = *(const f32x4*)(j.res + (size_t)(t0 + row) * 1024 + n0 + col + 4);
;         rv[0] = r0[0]; rv[1] = r0[1]; rv[2] = r0[2]; rv[3] = r0[3]; rv[4] = r1[0]; rv[5] = r1[1]; rv[6] = r1[2]; rv[7] = r1[3];
;       } else {
;         const u32x4 rb = *(const u32x4*)xq;
; #pragma unroll
;         for (int e = 0; e < 4; ++e) { rv[2 * e] = bflo(rb[e]); rv[2 * e + 1] = bfhi(rb[e]); }
;       }
;       float o[8]; float ss = 0.f;
; #pragma unroll
;       for (int e = 0; e < 4; ++e) { o[2 * e] = rv[2 * e] + bflo(av[e]); o[2 * e + 1] = rv[2 * e + 1] + bfhi(av[e]); ss += o[2 * e] * o[2 * e] + o[2 * e + 1] * o[2 * e + 1]; }
;       *(u32x4*)xq = (u32x4){pack2(o[0], o[1]), pack2(o[2], o[3]), pack2(o[4], o[5]), pack2(o[6], o[7])};
	v_lshlrev_b32_e32 v12, 16, v76
	v_and_b32_e32 v13, 0xffff0000, v76
	v_lshlrev_b32_e32 v28, 16, v77
	v_and_b32_e32 v29, 0xffff0000, v77
	v_lshlrev_b32_e32 v30, 16, v78
	v_and_b32_e32 v31, 0xffff0000, v78
	v_lshlrev_b32_e32 v128, 16, v79
	v_and_b32_e32 v129, 0xffff0000, v79
	v_lshlrev_b32_e32 v4, 16, v108
	v_and_b32_e32 v5, 0xffff0000, v108
	v_lshlrev_b32_e32 v6, 16, v109
	v_and_b32_e32 v7, 0xffff0000, v109
	v_lshlrev_b32_e32 v8, 16, v110
	v_and_b32_e32 v9, 0xffff0000, v110
	v_lshlrev_b32_e32 v10, 16, v111
	v_and_b32_e32 v11, 0xffff0000, v111
	v_add_f32_e32 v12, v12, v4
	v_add_f32_e32 v13, v13, v5
	v_add_f32_e32 v28, v28, v6
	v_add_f32_e32 v29, v29, v7
	v_add_f32_e32 v30, v30, v8
	v_add_f32_e32 v31, v31, v9
	v_add_f32_e32 v128, v128, v10
	v_add_f32_e32 v129, v129, v11
	v_mul_f32_e32 v153, v12, v12
	v_fmac_f32_e32 v153, v13, v13
	v_fmac_f32_e32 v153, v28, v28
	v_fmac_f32_e32 v153, v29, v29
	v_fmac_f32_e32 v153, v30, v30
	v_fmac_f32_e32 v153, v31, v31
	v_fmac_f32_e32 v153, v128, v128
	v_fmac_f32_e32 v153, v129, v129
	v_cvt_pk_bf16_f32 v76, v12, v13
	v_cvt_pk_bf16_f32 v77, v28, v29
	v_cvt_pk_bf16_f32 v78, v30, v31
	v_cvt_pk_bf16_f32 v79, v128, v129
	global_store_dwordx4 v[158:159], v[76:79], off offset:-1024
	s_waitcnt vmcnt(15) lgkmcnt(3)
	v_lshlrev_b32_e32 v12, 16, v80
	v_and_b32_e32 v13, 0xffff0000, v80
	v_lshlrev_b32_e32 v28, 16, v81
	v_and_b32_e32 v29, 0xffff0000, v81
	v_lshlrev_b32_e32 v30, 16, v82
	v_and_b32_e32 v31, 0xffff0000, v82
	v_lshlrev_b32_e32 v128, 16, v83
	v_and_b32_e32 v129, 0xffff0000, v83
	v_lshlrev_b32_e32 v4, 16, v112
	v_and_b32_e32 v5, 0xffff0000, v112
	v_lshlrev_b32_e32 v6, 16, v113
	v_and_b32_e32 v7, 0xffff0000, v113
	v_lshlrev_b32_e32 v8, 16, v114
	v_and_b32_e32 v9, 0xffff0000, v114
	v_lshlrev_b32_e32 v10, 16, v115
	v_and_b32_e32 v11, 0xffff0000, v115
	v_add_f32_e32 v12, v12, v4
	v_add_f32_e32 v13, v13, v5
	v_add_f32_e32 v28, v28, v6
	v_add_f32_e32 v29, v29, v7
	v_add_f32_e32 v30, v30, v8
	v_add_f32_e32 v31, v31, v9
	v_add_f32_e32 v128, v128, v10
	v_add_f32_e32 v129, v129, v11
	v_mul_f32_e32 v154, v12, v12
	v_fmac_f32_e32 v154, v13, v13
	v_fmac_f32_e32 v154, v28, v28
	v_fmac_f32_e32 v154, v29, v29
	v_fmac_f32_e32 v154, v30, v30
	v_fmac_f32_e32 v154, v31, v31
	v_fmac_f32_e32 v154, v128, v128
	v_fmac_f32_e32 v154, v129, v129
	v_cvt_pk_bf16_f32 v80, v12, v13
	v_cvt_pk_bf16_f32 v81, v28, v29
	v_cvt_pk_bf16_f32 v82, v30, v31
	v_cvt_pk_bf16_f32 v83, v128, v129
	global_store_dwordx4 v[158:159], v[80:83], off
	s_waitcnt vmcnt(15) lgkmcnt(2)
	v_lshlrev_b32_e32 v12, 16, v84
	v_and_b32_e32 v13, 0xffff0000, v84
	v_lshlrev_b32_e32 v28, 16, v85
	v_and_b32_e32 v29, 0xffff0000, v85
	v_lshlrev_b32_e32 v30, 16, v86
	v_and_b32_e32 v31, 0xffff0000, v86
	v_lshlrev_b32_e32 v128, 16, v87
	v_and_b32_e32 v129, 0xffff0000, v87
	v_lshlrev_b32_e32 v4, 16, v116
	v_and_b32_e32 v5, 0xffff0000, v116
	v_lshlrev_b32_e32 v6, 16, v117
	v_and_b32_e32 v7, 0xffff0000, v117
	v_lshlrev_b32_e32 v8, 16, v118
	v_and_b32_e32 v9, 0xffff0000, v118
	v_lshlrev_b32_e32 v10, 16, v119
	v_and_b32_e32 v11, 0xffff0000, v119
	v_add_f32_e32 v12, v12, v4
	v_add_f32_e32 v13, v13, v5
	v_add_f32_e32 v28, v28, v6
	v_add_f32_e32 v29, v29, v7
	v_add_f32_e32 v30, v30, v8
	v_add_f32_e32 v31, v31, v9
	v_add_f32_e32 v128, v128, v10
	v_add_f32_e32 v129, v129, v11
	v_mul_f32_e32 v155, v12, v12
	v_fmac_f32_e32 v155, v13, v13
	v_fmac_f32_e32 v155, v28, v28
	v_fmac_f32_e32 v155, v29, v29
	v_fmac_f32_e32 v155, v30, v30
	v_fmac_f32_e32 v155, v31, v31
	v_fmac_f32_e32 v155, v128, v128
	v_fmac_f32_e32 v155, v129, v129
	v_cvt_pk_bf16_f32 v84, v12, v13
	v_cvt_pk_bf16_f32 v85, v28, v29
	v_cvt_pk_bf16_f32 v86, v30, v31
	v_cvt_pk_bf16_f32 v87, v128, v129
	global_store_dwordx4 v[158:159], v[84:87], off offset:1024
	s_waitcnt vmcnt(15) lgkmcnt(1)
	v_lshlrev_b32_e32 v12, 16, v88
	v_and_b32_e32 v13, 0xffff0000, v88
	v_lshlrev_b32_e32 v28, 16, v89
	v_and_b32_e32 v29, 0xffff0000, v89
	v_lshlrev_b32_e32 v30, 16, v90
	v_and_b32_e32 v31, 0xffff0000, v90
	v_lshlrev_b32_e32 v128, 16, v91
	v_and_b32_e32 v129, 0xffff0000, v91
	v_lshlrev_b32_e32 v4, 16, v120
	v_and_b32_e32 v5, 0xffff0000, v120
	v_lshlrev_b32_e32 v6, 16, v121
	v_and_b32_e32 v7, 0xffff0000, v121
	v_lshlrev_b32_e32 v8, 16, v122
	v_and_b32_e32 v9, 0xffff0000, v122
	v_lshlrev_b32_e32 v10, 16, v123
	v_and_b32_e32 v11, 0xffff0000, v123
	v_add_f32_e32 v12, v12, v4
	v_add_f32_e32 v13, v13, v5
	v_add_f32_e32 v28, v28, v6
	v_add_f32_e32 v29, v29, v7
	v_add_f32_e32 v30, v30, v8
	v_add_f32_e32 v31, v31, v9
	v_add_f32_e32 v128, v128, v10
	v_add_f32_e32 v129, v129, v11
	v_mul_f32_e32 v156, v12, v12
	v_fmac_f32_e32 v156, v13, v13
	v_fmac_f32_e32 v156, v28, v28
	v_fmac_f32_e32 v156, v29, v29
	v_fmac_f32_e32 v156, v30, v30
	v_fmac_f32_e32 v156, v31, v31
	v_fmac_f32_e32 v156, v128, v128
	v_fmac_f32_e32 v156, v129, v129
	v_cvt_pk_bf16_f32 v88, v12, v13
	v_cvt_pk_bf16_f32 v89, v28, v29
	v_cvt_pk_bf16_f32 v90, v30, v31
	v_cvt_pk_bf16_f32 v91, v128, v129
	global_store_dwordx4 v[158:159], v[88:91], off offset:2048
	s_waitcnt vmcnt(15) lgkmcnt(0)
	v_lshlrev_b32_e32 v12, 16, v92
	v_and_b32_e32 v13, 0xffff0000, v92
	v_lshlrev_b32_e32 v28, 16, v93
	v_and_b32_e32 v29, 0xffff0000, v93
	v_lshlrev_b32_e32 v30, 16, v94
	v_and_b32_e32 v31, 0xffff0000, v94
	v_lshlrev_b32_e32 v128, 16, v95
	v_and_b32_e32 v129, 0xffff0000, v95
	v_lshlrev_b32_e32 v4, 16, v124
	v_and_b32_e32 v5, 0xffff0000, v124
	v_lshlrev_b32_e32 v6, 16, v125
	v_and_b32_e32 v7, 0xffff0000, v125
	v_lshlrev_b32_e32 v8, 16, v126
	v_and_b32_e32 v9, 0xffff0000, v126
	v_lshlrev_b32_e32 v10, 16, v127
	v_and_b32_e32 v11, 0xffff0000, v127
	v_add_f32_e32 v12, v12, v4
	v_add_f32_e32 v13, v13, v5
	v_add_f32_e32 v28, v28, v6
	v_add_f32_e32 v29, v29, v7
	v_add_f32_e32 v30, v30, v8
	v_add_f32_e32 v31, v31, v9
	v_add_f32_e32 v128, v128, v10
	v_add_f32_e32 v129, v129, v11
	v_mul_f32_e32 v157, v12, v12
	v_fmac_f32_e32 v157, v13, v13
	v_fmac_f32_e32 v157, v28, v28
	v_fmac_f32_e32 v157, v29, v29
	v_fmac_f32_e32 v157, v30, v30
	v_fmac_f32_e32 v157, v31, v31
	v_fmac_f32_e32 v157, v128, v128
	v_fmac_f32_e32 v157, v129, v129
	v_cvt_pk_bf16_f32 v92, v12, v13
	v_cvt_pk_bf16_f32 v93, v28, v29
	v_cvt_pk_bf16_f32 v94, v30, v31
	v_cvt_pk_bf16_f32 v95, v128, v129
	global_store_dwordx4 v[158:159], v[92:95], off offset:3072
	s_branch .Lepi_out_sums
; DI unsigned pack2(float a, float b) { f32x2 v = {a, b}; bf16x2_t r = __builtin_convertvector(v, bf16x2_t); return __builtin_bit_cast(unsigned, r); }
; DI float bflo(unsigned v) { return __uint_as_float(v << 16); }
; DI float bfhi(unsigned v) { return __uint_as_float(v & 0xffff0000u); }
; DI void gemm_tile(const Params& p, const GemmJob& j, int mt, int nt, char* smem) {
;     ...
;       if (j.res) {
;         const f32x4 r0 = *(const f32x4*)(j.res + (size_t)(t0 + row) * 1024 + n0 + col), r1 = *(const f32x4*)(j.res + (size_t)(t0 + row) * 1024 + n0 + col + 4);
;         rv[0] = r0[0]; rv[1] = r0[1]; rv[2] = r0[2]; rv[3] = r0[3]; rv[4] = r1[0]; rv[5] = r1[1]; rv[6] = r1[2]; rv[7] = r1[3];
;       } else {
;         const u32x4 rb = *(const u32x4*)xq;
; #pragma unroll
;         for (int e = 0; e < 4; ++e) { rv[2 * e] = bflo(rb[e]); rv[2 * e + 1] = bfhi(rb[e]); }
;       }
;       float o[8]; float ss = 0.f;
; #pragma unroll
;       for (int e = 0; e < 4; ++e) { o[2 * e] = rv[2 * e] + bflo(av[e]); o[2 * e + 1] = rv[2 * e + 1] + bfhi(av[e]); ss += o[2 * e] * o[2 * e] + o[2 * e + 1] * o[2 * e + 1]; }
;       *(u32x4*)xq = (u32x4){pack2(o[0], o[1]), pack2(o[2], o[3]), pack2(o[4], o[5]), pack2(o[6], o[7])};
.Lepi_out_res:
	v_lshlrev_b64 v[28:29], 12, v[20:21]
	v_lshl_add_u64 v[28:29], v[18:19], 0, v[28:29]
	s_mov_b64 s[6:7], 0x10000
	global_load_dwordx4 v[32:35], v[28:29], off
	global_load_dwordx4 v[36:39], v[28:29], off offset:16
	v_lshl_add_u64 v[28:29], v[28:29], 0, s[6:7]
	global_load_dwordx4 v[40:43], v[28:29], off
	global_load_dwordx4 v[44:47], v[28:29], off offset:16
	v_lshl_add_u64 v[28:29], v[28:29], 0, s[6:7]
	global_load_dwordx4 v[48:51], v[28:29], off
	global_load_dwordx4 v[52:55], v[28:29], off offset:16
	v_lshl_add_u64 v[28:29], v[28:29], 0, s[6:7]
	global_load_dwordx4 v[56:59], v[28:29], off
	global_load_dwordx4 v[60:63], v[28:29], off offset:16
	v_lshl_add_u64 v[28:29], v[28:29], 0, s[6:7]
	global_load_dwordx4 v[64:67], v[28:29], off
	global_load_dwordx4 v[68:71], v[28:29], off offset:16
	v_lshl_add_u64 v[28:29], v[28:29], 0, s[6:7]
	global_load_dwordx4 v[72:75], v[28:29], off
	global_load_dwordx4 v[76:79], v[28:29], off offset:16
	v_lshl_add_u64 v[28:29], v[28:29], 0, s[6:7]
	global_load_dwordx4 v[80:83], v[28:29], off
	global_load_dwordx4 v[84:87], v[28:29], off offset:16
	v_lshl_add_u64 v[28:29], v[28:29], 0, s[6:7]
	global_load_dwordx4 v[88:91], v[28:29], off
	global_load_dwordx4 v[92:95], v[28:29], off offset:16
	v_lshl_add_u64 v[28:29], v[28:29], 0, s[6:7]
	ds_read_b128 v[96:99], v2
	ds_read_b128 v[100:103], v2 offset:4352
	ds_read_b128 v[104:107], v2 offset:8704
	ds_read_b128 v[108:111], v2 offset:13056
	ds_read_b128 v[112:115], v2 offset:17408
	ds_read_b128 v[116:119], v2 offset:21760
	ds_read_b128 v[120:123], v2 offset:26112
	ds_read_b128 v[124:127], v2 offset:30464
	s_waitcnt vmcnt(14) lgkmcnt(7)
	v_lshlrev_b32_e32 v4, 16, v96
	v_and_b32_e32 v5, 0xffff0000, v96
	v_lshlrev_b32_e32 v6, 16, v97
	v_and_b32_e32 v7, 0xffff0000, v97
	v_lshlrev_b32_e32 v8, 16, v98
	v_and_b32_e32 v9, 0xffff0000, v98
	v_lshlrev_b32_e32 v10, 16, v99
	v_and_b32_e32 v11, 0xffff0000, v99
	v_add_f32_e32 v32, v32, v4
	v_add_f32_e32 v33, v33, v5
	v_add_f32_e32 v34, v34, v6
	v_add_f32_e32 v35, v35, v7
	v_add_f32_e32 v36, v36, v8
	v_add_f32_e32 v37, v37, v9
	v_add_f32_e32 v38, v38, v10
	v_add_f32_e32 v39, v39, v11
	v_mul_f32_e32 v142, v32, v32
	v_fmac_f32_e32 v142, v33, v33
	v_fmac_f32_e32 v142, v34, v34
	v_fmac_f32_e32 v142, v35, v35
	v_fmac_f32_e32 v142, v36, v36
	v_fmac_f32_e32 v142, v37, v37
	v_fmac_f32_e32 v142, v38, v38
	v_fmac_f32_e32 v142, v39, v39
	v_cvt_pk_bf16_f32 v32, v32, v33
	v_cvt_pk_bf16_f32 v33, v34, v35
	v_cvt_pk_bf16_f32 v34, v36, v37
	v_cvt_pk_bf16_f32 v35, v38, v39
	global_store_dwordx4 v[22:23], v[32:35], off offset:-4096
	s_waitcnt vmcnt(13) lgkmcnt(6)
	v_lshlrev_b32_e32 v4, 16, v100
	v_and_b32_e32 v5, 0xffff0000, v100
	v_lshlrev_b32_e32 v6, 16, v101
	v_and_b32_e32 v7, 0xffff0000, v101
	v_lshlrev_b32_e32 v8, 16, v102
	v_and_b32_e32 v9, 0xffff0000, v102
	v_lshlrev_b32_e32 v10, 16, v103
	v_and_b32_e32 v11, 0xffff0000, v103
	v_add_f32_e32 v40, v40, v4
	v_add_f32_e32 v41, v41, v5
	v_add_f32_e32 v42, v42, v6
	v_add_f32_e32 v43, v43, v7
	v_add_f32_e32 v44, v44, v8
	v_add_f32_e32 v45, v45, v9
	v_add_f32_e32 v46, v46, v10
	v_add_f32_e32 v47, v47, v11
	v_mul_f32_e32 v143, v40, v40
	v_fmac_f32_e32 v143, v41, v41
	v_fmac_f32_e32 v143, v42, v42
	v_fmac_f32_e32 v143, v43, v43
	v_fmac_f32_e32 v143, v44, v44
	v_fmac_f32_e32 v143, v45, v45
	v_fmac_f32_e32 v143, v46, v46
	v_fmac_f32_e32 v143, v47, v47
	v_cvt_pk_bf16_f32 v40, v40, v41
	v_cvt_pk_bf16_f32 v41, v42, v43
	v_cvt_pk_bf16_f32 v42, v44, v45
	v_cvt_pk_bf16_f32 v43, v46, v47
	global_store_dwordx4 v[22:23], v[40:43], off offset:-3072
	s_waitcnt vmcnt(12) lgkmcnt(5)
	v_lshlrev_b32_e32 v4, 16, v104
	v_and_b32_e32 v5, 0xffff0000, v104
	v_lshlrev_b32_e32 v6, 16, v105
	v_and_b32_e32 v7, 0xffff0000, v105
	v_lshlrev_b32_e32 v8, 16, v106
	v_and_b32_e32 v9, 0xffff0000, v106
	v_lshlrev_b32_e32 v10, 16, v107
	v_and_b32_e32 v11, 0xffff0000, v107
	v_add_f32_e32 v48, v48, v4
	v_add_f32_e32 v49, v49, v5
	v_add_f32_e32 v50, v50, v6
	v_add_f32_e32 v51, v51, v7
	v_add_f32_e32 v52, v52, v8
	v_add_f32_e32 v53, v53, v9
	v_add_f32_e32 v54, v54, v10
	v_add_f32_e32 v55, v55, v11
	v_mul_f32_e32 v144, v48, v48
	v_fmac_f32_e32 v144, v49, v49
	v_fmac_f32_e32 v144, v50, v50
	v_fmac_f32_e32 v144, v51, v51
	v_fmac_f32_e32 v144, v52, v52
	v_fmac_f32_e32 v144, v53, v53
	v_fmac_f32_e32 v144, v54, v54
	v_fmac_f32_e32 v144, v55, v55
	v_cvt_pk_bf16_f32 v48, v48, v49
	v_cvt_pk_bf16_f32 v49, v50, v51
	v_cvt_pk_bf16_f32 v50, v52, v53
	v_cvt_pk_bf16_f32 v51, v54, v55
	global_store_dwordx4 v[22:23], v[48:51], off offset:-2048
	s_waitcnt vmcnt(11) lgkmcnt(4)
	v_lshlrev_b32_e32 v4, 16, v108
	v_and_b32_e32 v5, 0xffff0000, v108
	v_lshlrev_b32_e32 v6, 16, v109
	v_and_b32_e32 v7, 0xffff0000, v109
	v_lshlrev_b32_e32 v8, 16, v110
	v_and_b32_e32 v9, 0xffff0000, v110
	v_lshlrev_b32_e32 v10, 16, v111
	v_and_b32_e32 v11, 0xffff0000, v111
	v_add_f32_e32 v56, v56, v4
	v_add_f32_e32 v57, v57, v5
	v_add_f32_e32 v58, v58, v6
	v_add_f32_e32 v59, v59, v7
	v_add_f32_e32 v60, v60, v8
	v_add_f32_e32 v61, v61, v9
	v_add_f32_e32 v62, v62, v10
	v_add_f32_e32 v63, v63, v11
	v_mul_f32_e32 v145, v56, v56
	v_fmac_f32_e32 v145, v57, v57
	v_fmac_f32_e32 v145, v58, v58
	v_fmac_f32_e32 v145, v59, v59
	v_fmac_f32_e32 v145, v60, v60
	v_fmac_f32_e32 v145, v61, v61
	v_fmac_f32_e32 v145, v62, v62
	v_fmac_f32_e32 v145, v63, v63
	v_cvt_pk_bf16_f32 v56, v56, v57
	v_cvt_pk_bf16_f32 v57, v58, v59
	v_cvt_pk_bf16_f32 v58, v60, v61
	v_cvt_pk_bf16_f32 v59, v62, v63
	global_store_dwordx4 v[22:23], v[56:59], off offset:-1024
	s_waitcnt vmcnt(10) lgkmcnt(3)
; DI unsigned pack2(float a, float b) { f32x2 v = {a, b}; bf16x2_t r = __builtin_convertvector(v, bf16x2_t); return __builtin_bit_cast(unsigned, r); }
; DI float bflo(unsigned v) { return __uint_as_float(v << 16); }
; DI float bfhi(unsigned v) { return __uint_as_float(v & 0xffff0000u); }
; DI void gemm_tile(const Params& p, const GemmJob& j, int mt, int nt, char* smem) {
;     ...
;       if (j.res) {
;         const f32x4 r0 = *(const f32x4*)(j.res + (size_t)(t0 + row) * 1024 + n0 + col), r1 = *(const f32x4*)(j.res + (size_t)(t0 + row) * 1024 + n0 + col + 4);
;         rv[0] = r0[0]; rv[1] = r0[1]; rv[2] = r0[2]; rv[3] = r0[3]; rv[4] = r1[0]; rv[5] = r1[1]; rv[6] = r1[2]; rv[7] = r1[3];
;       } else {
;         const u32x4 rb = *(const u32x4*)xq;
; #pragma unroll
;         for (int e = 0; e < 4; ++e) { rv[2 * e] = bflo(rb[e]); rv[2 * e + 1] = bfhi(rb[e]); }
;       }
;       float o[8]; float ss = 0.f;
; #pragma unroll
;       for (int e = 0; e < 4; ++e) { o[2 * e] = rv[2 * e] + bflo(av[e]); o[2 * e + 1] = rv[2 * e + 1] + bfhi(av[e]); ss += o[2 * e] * o[2 * e] + o[2 * e + 1] * o[2 * e + 1]; }
;       *(u32x4*)xq = (u32x4){pack2(o[0], o[1]), pack2(o[2], o[3]), pack2(o[4], o[5]), pack2(o[6], o[7])};
	v_lshlrev_b32_e32 v4, 16, v112
	v_and_b32_e32 v5, 0xffff0000, v112
	v_lshlrev_b32_e32 v6, 16, v113
	v_and_b32_e32 v7, 0xffff0000, v113
	v_lshlrev_b32_e32 v8, 16, v114
	v_and_b32_e32 v9, 0xffff0000, v114
	v_lshlrev_b32_e32 v10, 16, v115
	v_and_b32_e32 v11, 0xffff0000, v115
	v_add_f32_e32 v64, v64, v4
	v_add_f32_e32 v65, v65, v5
	v_add_f32_e32 v66, v66, v6
	v_add_f32_e32 v67, v67, v7
	v_add_f32_e32 v68, v68, v8
	v_add_f32_e32 v69, v69, v9
	v_add_f32_e32 v70, v70, v10
	v_add_f32_e32 v71, v71, v11
	v_mul_f32_e32 v146, v64, v64
	v_fmac_f32_e32 v146, v65, v65
	v_fmac_f32_e32 v146, v66, v66
	v_fmac_f32_e32 v146, v67, v67
	v_fmac_f32_e32 v146, v68, v68
	v_fmac_f32_e32 v146, v69, v69
	v_fmac_f32_e32 v146, v70, v70
	v_fmac_f32_e32 v146, v71, v71
	v_cvt_pk_bf16_f32 v64, v64, v65
	v_cvt_pk_bf16_f32 v65, v66, v67
	v_cvt_pk_bf16_f32 v66, v68, v69
	v_cvt_pk_bf16_f32 v67, v70, v71
	global_store_dwordx4 v[22:23], v[64:67], off
	s_waitcnt vmcnt(9) lgkmcnt(2)
	v_lshlrev_b32_e32 v4, 16, v116
	v_and_b32_e32 v5, 0xffff0000, v116
	v_lshlrev_b32_e32 v6, 16, v117
	v_and_b32_e32 v7, 0xffff0000, v117
	v_lshlrev_b32_e32 v8, 16, v118
	v_and_b32_e32 v9, 0xffff0000, v118
	v_lshlrev_b32_e32 v10, 16, v119
	v_and_b32_e32 v11, 0xffff0000, v119
	v_add_f32_e32 v72, v72, v4
	v_add_f32_e32 v73, v73, v5
	v_add_f32_e32 v74, v74, v6
	v_add_f32_e32 v75, v75, v7
	v_add_f32_e32 v76, v76, v8
	v_add_f32_e32 v77, v77, v9
	v_add_f32_e32 v78, v78, v10
	v_add_f32_e32 v79, v79, v11
	v_mul_f32_e32 v147, v72, v72
	v_fmac_f32_e32 v147, v73, v73
	v_fmac_f32_e32 v147, v74, v74
	v_fmac_f32_e32 v147, v75, v75
	v_fmac_f32_e32 v147, v76, v76
	v_fmac_f32_e32 v147, v77, v77
	v_fmac_f32_e32 v147, v78, v78
	v_fmac_f32_e32 v147, v79, v79
	v_cvt_pk_bf16_f32 v72, v72, v73
	v_cvt_pk_bf16_f32 v73, v74, v75
	v_cvt_pk_bf16_f32 v74, v76, v77
	v_cvt_pk_bf16_f32 v75, v78, v79
	global_store_dwordx4 v[22:23], v[72:75], off offset:1024
	s_waitcnt vmcnt(8) lgkmcnt(1)
	v_lshlrev_b32_e32 v4, 16, v120
	v_and_b32_e32 v5, 0xffff0000, v120
	v_lshlrev_b32_e32 v6, 16, v121
	v_and_b32_e32 v7, 0xffff0000, v121
	v_lshlrev_b32_e32 v8, 16, v122
	v_and_b32_e32 v9, 0xffff0000, v122
	v_lshlrev_b32_e32 v10, 16, v123
	v_and_b32_e32 v11, 0xffff0000, v123
	v_add_f32_e32 v80, v80, v4
	v_add_f32_e32 v81, v81, v5
	v_add_f32_e32 v82, v82, v6
	v_add_f32_e32 v83, v83, v7
	v_add_f32_e32 v84, v84, v8
	v_add_f32_e32 v85, v85, v9
	v_add_f32_e32 v86, v86, v10
	v_add_f32_e32 v87, v87, v11
	v_mul_f32_e32 v148, v80, v80
	v_fmac_f32_e32 v148, v81, v81
	v_fmac_f32_e32 v148, v82, v82
	v_fmac_f32_e32 v148, v83, v83
	v_fmac_f32_e32 v148, v84, v84
	v_fmac_f32_e32 v148, v85, v85
	v_fmac_f32_e32 v148, v86, v86
	v_fmac_f32_e32 v148, v87, v87
	v_cvt_pk_bf16_f32 v80, v80, v81
	v_cvt_pk_bf16_f32 v81, v82, v83
	v_cvt_pk_bf16_f32 v82, v84, v85
	v_cvt_pk_bf16_f32 v83, v86, v87
	global_store_dwordx4 v[22:23], v[80:83], off offset:2048
	s_waitcnt vmcnt(7) lgkmcnt(0)
	v_lshlrev_b32_e32 v4, 16, v124
	v_and_b32_e32 v5, 0xffff0000, v124
	v_lshlrev_b32_e32 v6, 16, v125
	v_and_b32_e32 v7, 0xffff0000, v125
	v_lshlrev_b32_e32 v8, 16, v126
	v_and_b32_e32 v9, 0xffff0000, v126
	v_lshlrev_b32_e32 v10, 16, v127
	v_and_b32_e32 v11, 0xffff0000, v127
	v_add_f32_e32 v88, v88, v4
	v_add_f32_e32 v89, v89, v5
	v_add_f32_e32 v90, v90, v6
	v_add_f32_e32 v91, v91, v7
	v_add_f32_e32 v92, v92, v8
	v_add_f32_e32 v93, v93, v9
	v_add_f32_e32 v94, v94, v10
	v_add_f32_e32 v95, v95, v11
	v_mul_f32_e32 v149, v88, v88
	v_fmac_f32_e32 v149, v89, v89
	v_fmac_f32_e32 v149, v90, v90
	v_fmac_f32_e32 v149, v91, v91
	v_fmac_f32_e32 v149, v92, v92
	v_fmac_f32_e32 v149, v93, v93
	v_fmac_f32_e32 v149, v94, v94
	v_fmac_f32_e32 v149, v95, v95
	v_cvt_pk_bf16_f32 v88, v88, v89
	v_cvt_pk_bf16_f32 v89, v90, v91
	v_cvt_pk_bf16_f32 v90, v92, v93
	v_cvt_pk_bf16_f32 v91, v94, v95
	global_store_dwordx4 v[22:23], v[88:91], off offset:3072
	global_load_dwordx4 v[32:35], v[28:29], off
	global_load_dwordx4 v[36:39], v[28:29], off offset:16
	v_lshl_add_u64 v[28:29], v[28:29], 0, s[6:7]
	global_load_dwordx4 v[40:43], v[28:29], off
	global_load_dwordx4 v[44:47], v[28:29], off offset:16
	v_lshl_add_u64 v[28:29], v[28:29], 0, s[6:7]
	global_load_dwordx4 v[48:51], v[28:29], off
	global_load_dwordx4 v[52:55], v[28:29], off offset:16
	v_lshl_add_u64 v[28:29], v[28:29], 0, s[6:7]
	global_load_dwordx4 v[56:59], v[28:29], off
	global_load_dwordx4 v[60:63], v[28:29], off offset:16
	v_lshl_add_u64 v[28:29], v[28:29], 0, s[6:7]
	global_load_dwordx4 v[64:67], v[28:29], off
	global_load_dwordx4 v[68:71], v[28:29], off offset:16
	v_lshl_add_u64 v[28:29], v[28:29], 0, s[6:7]
	global_load_dwordx4 v[72:75], v[28:29], off
	global_load_dwordx4 v[76:79], v[28:29], off offset:16
	v_lshl_add_u64 v[28:29], v[28:29], 0, s[6:7]
	global_load_dwordx4 v[80:83], v[28:29], off
	global_load_dwordx4 v[84:87], v[28:29], off offset:16
	v_lshl_add_u64 v[28:29], v[28:29], 0, s[6:7]
	global_load_dwordx4 v[88:91], v[28:29], off
	global_load_dwordx4 v[92:95], v[28:29], off offset:16
	v_lshl_add_u64 v[28:29], v[28:29], 0, s[6:7]
	ds_read_b128 v[96:99], v2 offset:34816
	ds_read_b128 v[100:103], v2 offset:39168
	ds_read_b128 v[104:107], v2 offset:43520
	ds_read_b128 v[108:111], v2 offset:47872
	ds_read_b128 v[112:115], v2 offset:52224
	ds_read_b128 v[116:119], v2 offset:56576
	ds_read_b128 v[120:123], v2 offset:60928
	ds_read_b128 v[124:127], v2 offset:65280
	s_waitcnt vmcnt(14) lgkmcnt(7)
; DI unsigned pack2(float a, float b) { f32x2 v = {a, b}; bf16x2_t r = __builtin_convertvector(v, bf16x2_t); return __builtin_bit_cast(unsigned, r); }
; DI float bflo(unsigned v) { return __uint_as_float(v << 16); }
; DI float bfhi(unsigned v) { return __uint_as_float(v & 0xffff0000u); }
; DI void gemm_tile(const Params& p, const GemmJob& j, int mt, int nt, char* smem) {
;     ...
;       if (j.res) {
;         const f32x4 r0 = *(const f32x4*)(j.res + (size_t)(t0 + row) * 1024 + n0 + col), r1 = *(const f32x4*)(j.res + (size_t)(t0 + row) * 1024 + n0 + col + 4);
;         rv[0] = r0[0]; rv[1] = r0[1]; rv[2] = r0[2]; rv[3] = r0[3]; rv[4] = r1[0]; rv[5] = r1[1]; rv[6] = r1[2]; rv[7] = r1[3];
;       } else {
;         const u32x4 rb = *(const u32x4*)xq;
; #pragma unroll
;         for (int e = 0; e < 4; ++e) { rv[2 * e] = bflo(rb[e]); rv[2 * e + 1] = bfhi(rb[e]); }
;       }
;       float o[8]; float ss = 0.f;
; #pragma unroll
;       for (int e = 0; e < 4; ++e) { o[2 * e] = rv[2 * e] + bflo(av[e]); o[2 * e + 1] = rv[2 * e + 1] + bfhi(av[e]); ss += o[2 * e] * o[2 * e] + o[2 * e + 1] * o[2 * e + 1]; }
;       *(u32x4*)xq = (u32x4){pack2(o[0], o[1]), pack2(o[2], o[3]), pack2(o[4], o[5]), pack2(o[6], o[7])};
	v_lshlrev_b32_e32 v4, 16, v96
	v_and_b32_e32 v5, 0xffff0000, v96
	v_lshlrev_b32_e32 v6, 16, v97
	v_and_b32_e32 v7, 0xffff0000, v97
	v_lshlrev_b32_e32 v8, 16, v98
	v_and_b32_e32 v9, 0xffff0000, v98
	v_lshlrev_b32_e32 v10, 16, v99
	v_and_b32_e32 v11, 0xffff0000, v99
	v_add_f32_e32 v32, v32, v4
	v_add_f32_e32 v33, v33, v5
	v_add_f32_e32 v34, v34, v6
	v_add_f32_e32 v35, v35, v7
	v_add_f32_e32 v36, v36, v8
	v_add_f32_e32 v37, v37, v9
	v_add_f32_e32 v38, v38, v10
	v_add_f32_e32 v39, v39, v11
	v_mul_f32_e32 v150, v32, v32
	v_fmac_f32_e32 v150, v33, v33
	v_fmac_f32_e32 v150, v34, v34
	v_fmac_f32_e32 v150, v35, v35
	v_fmac_f32_e32 v150, v36, v36
	v_fmac_f32_e32 v150, v37, v37
	v_fmac_f32_e32 v150, v38, v38
	v_fmac_f32_e32 v150, v39, v39
	v_cvt_pk_bf16_f32 v32, v32, v33
	v_cvt_pk_bf16_f32 v33, v34, v35
	v_cvt_pk_bf16_f32 v34, v36, v37
	v_cvt_pk_bf16_f32 v35, v38, v39
	global_store_dwordx4 v[158:159], v[32:35], off offset:-4096
	s_waitcnt vmcnt(13) lgkmcnt(6)
	v_lshlrev_b32_e32 v4, 16, v100
	v_and_b32_e32 v5, 0xffff0000, v100
	v_lshlrev_b32_e32 v6, 16, v101
	v_and_b32_e32 v7, 0xffff0000, v101
	v_lshlrev_b32_e32 v8, 16, v102
	v_and_b32_e32 v9, 0xffff0000, v102
	v_lshlrev_b32_e32 v10, 16, v103
	v_and_b32_e32 v11, 0xffff0000, v103
	v_add_f32_e32 v40, v40, v4
	v_add_f32_e32 v41, v41, v5
	v_add_f32_e32 v42, v42, v6
	v_add_f32_e32 v43, v43, v7
	v_add_f32_e32 v44, v44, v8
	v_add_f32_e32 v45, v45, v9
	v_add_f32_e32 v46, v46, v10
	v_add_f32_e32 v47, v47, v11
	v_mul_f32_e32 v151, v40, v40
	v_fmac_f32_e32 v151, v41, v41
	v_fmac_f32_e32 v151, v42, v42
	v_fmac_f32_e32 v151, v43, v43
	v_fmac_f32_e32 v151, v44, v44
	v_fmac_f32_e32 v151, v45, v45
	v_fmac_f32_e32 v151, v46, v46
	v_fmac_f32_e32 v151, v47, v47
	v_cvt_pk_bf16_f32 v40, v40, v41
	v_cvt_pk_bf16_f32 v41, v42, v43
	v_cvt_pk_bf16_f32 v42, v44, v45
	v_cvt_pk_bf16_f32 v43, v46, v47
	global_store_dwordx4 v[158:159], v[40:43], off offset:-3072
	s_waitcnt vmcnt(12) lgkmcnt(5)
	v_lshlrev_b32_e32 v4, 16, v104
	v_and_b32_e32 v5, 0xffff0000, v104
	v_lshlrev_b32_e32 v6, 16, v105
	v_and_b32_e32 v7, 0xffff0000, v105
	v_lshlrev_b32_e32 v8, 16, v106
	v_and_b32_e32 v9, 0xffff0000, v106
	v_lshlrev_b32_e32 v10, 16, v107
	v_and_b32_e32 v11, 0xffff0000, v107
	v_add_f32_e32 v48, v48, v4
	v_add_f32_e32 v49, v49, v5
	v_add_f32_e32 v50, v50, v6
	v_add_f32_e32 v51, v51, v7
	v_add_f32_e32 v52, v52, v8
	v_add_f32_e32 v53, v53, v9
	v_add_f32_e32 v54, v54, v10
	v_add_f32_e32 v55, v55, v11
	v_mul_f32_e32 v152, v48, v48
	v_fmac_f32_e32 v152, v49, v49
	v_fmac_f32_e32 v152, v50, v50
	v_fmac_f32_e32 v152, v51, v51
	v_fmac_f32_e32 v152, v52, v52
	v_fmac_f32_e32 v152, v53, v53
	v_fmac_f32_e32 v152, v54, v54
	v_fmac_f32_e32 v152, v55, v55
	v_cvt_pk_bf16_f32 v48, v48, v49
	v_cvt_pk_bf16_f32 v49, v50, v51
	v_cvt_pk_bf16_f32 v50, v52, v53
	v_cvt_pk_bf16_f32 v51, v54, v55
	global_store_dwordx4 v[158:159], v[48:51], off offset:-2048
	s_waitcnt vmcnt(11) lgkmcnt(4)
	v_lshlrev_b32_e32 v4, 16, v108
	v_and_b32_e32 v5, 0xffff0000, v108
	v_lshlrev_b32_e32 v6, 16, v109
	v_and_b32_e32 v7, 0xffff0000, v109
	v_lshlrev_b32_e32 v8, 16, v110
	v_and_b32_e32 v9, 0xffff0000, v110
	v_lshlrev_b32_e32 v10, 16, v111
	v_and_b32_e32 v11, 0xffff0000, v111
	v_add_f32_e32 v56, v56, v4
	v_add_f32_e32 v57, v57, v5
	v_add_f32_e32 v58, v58, v6
	v_add_f32_e32 v59, v59, v7
	v_add_f32_e32 v60, v60, v8
	v_add_f32_e32 v61, v61, v9
	v_add_f32_e32 v62, v62, v10
	v_add_f32_e32 v63, v63, v11
	v_mul_f32_e32 v153, v56, v56
	v_fmac_f32_e32 v153, v57, v57
	v_fmac_f32_e32 v153, v58, v58
	v_fmac_f32_e32 v153, v59, v59
	v_fmac_f32_e32 v153, v60, v60
	v_fmac_f32_e32 v153, v61, v61
	v_fmac_f32_e32 v153, v62, v62
	v_fmac_f32_e32 v153, v63, v63
	v_cvt_pk_bf16_f32 v56, v56, v57
	v_cvt_pk_bf16_f32 v57, v58, v59
	v_cvt_pk_bf16_f32 v58, v60, v61
	v_cvt_pk_bf16_f32 v59, v62, v63
	global_store_dwordx4 v[158:159], v[56:59], off offset:-1024
	s_waitcnt vmcnt(10) lgkmcnt(3)
	v_lshlrev_b32_e32 v4, 16, v112
	v_and_b32_e32 v5, 0xffff0000, v112
	v_lshlrev_b32_e32 v6, 16, v113
	v_and_b32_e32 v7, 0xffff0000, v113
	v_lshlrev_b32_e32 v8, 16, v114
	v_and_b32_e32 v9, 0xffff0000, v114
	v_lshlrev_b32_e32 v10, 16, v115
	v_and_b32_e32 v11, 0xffff0000, v115
	v_add_f32_e32 v64, v64, v4
	v_add_f32_e32 v65, v65, v5
	v_add_f32_e32 v66, v66, v6
	v_add_f32_e32 v67, v67, v7
	v_add_f32_e32 v68, v68, v8
	v_add_f32_e32 v69, v69, v9
	v_add_f32_e32 v70, v70, v10
	v_add_f32_e32 v71, v71, v11
	v_mul_f32_e32 v154, v64, v64
	v_fmac_f32_e32 v154, v65, v65
	v_fmac_f32_e32 v154, v66, v66
	v_fmac_f32_e32 v154, v67, v67
	v_fmac_f32_e32 v154, v68, v68
	v_fmac_f32_e32 v154, v69, v69
	v_fmac_f32_e32 v154, v70, v70
	v_fmac_f32_e32 v154, v71, v71
	v_cvt_pk_bf16_f32 v64, v64, v65
	v_cvt_pk_bf16_f32 v65, v66, v67
	v_cvt_pk_bf16_f32 v66, v68, v69
	v_cvt_pk_bf16_f32 v67, v70, v71
	global_store_dwordx4 v[158:159], v[64:67], off
	s_waitcnt vmcnt(9) lgkmcnt(2)
	v_lshlrev_b32_e32 v4, 16, v116
	v_and_b32_e32 v5, 0xffff0000, v116
	v_lshlrev_b32_e32 v6, 16, v117
	v_and_b32_e32 v7, 0xffff0000, v117
	v_lshlrev_b32_e32 v8, 16, v118
	v_and_b32_e32 v9, 0xffff0000, v118
	v_lshlrev_b32_e32 v10, 16, v119
	v_and_b32_e32 v11, 0xffff0000, v119
	v_add_f32_e32 v72, v72, v4
	v_add_f32_e32 v73, v73, v5
	v_add_f32_e32 v74, v74, v6
	v_add_f32_e32 v75, v75, v7
	v_add_f32_e32 v76, v76, v8
	v_add_f32_e32 v77, v77, v9
	v_add_f32_e32 v78, v78, v10
	v_add_f32_e32 v79, v79, v11
	v_mul_f32_e32 v155, v72, v72
	v_fmac_f32_e32 v155, v73, v73
	v_fmac_f32_e32 v155, v74, v74
	v_fmac_f32_e32 v155, v75, v75
	v_fmac_f32_e32 v155, v76, v76
	v_fmac_f32_e32 v155, v77, v77
	v_fmac_f32_e32 v155, v78, v78
	v_fmac_f32_e32 v155, v79, v79
	v_cvt_pk_bf16_f32 v72, v72, v73
	v_cvt_pk_bf16_f32 v73, v74, v75
	v_cvt_pk_bf16_f32 v74, v76, v77
	v_cvt_pk_bf16_f32 v75, v78, v79
	global_store_dwordx4 v[158:159], v[72:75], off offset:1024
	s_waitcnt vmcnt(8) lgkmcnt(1)
; DI unsigned pack2(float a, float b) { f32x2 v = {a, b}; bf16x2_t r = __builtin_convertvector(v, bf16x2_t); return __builtin_bit_cast(unsigned, r); }
; DI float bflo(unsigned v) { return __uint_as_float(v << 16); }
; DI float bfhi(unsigned v) { return __uint_as_float(v & 0xffff0000u); }
; DI void gemm_tile(const Params& p, const GemmJob& j, int mt, int nt, char* smem) {
;     ...
;       if (j.res) {
;         const f32x4 r0 = *(const f32x4*)(j.res + (size_t)(t0 + row) * 1024 + n0 + col), r1 = *(const f32x4*)(j.res + (size_t)(t0 + row) * 1024 + n0 + col + 4);
;         rv[0] = r0[0]; rv[1] = r0[1]; rv[2] = r0[2]; rv[3] = r0[3]; rv[4] = r1[0]; rv[5] = r1[1]; rv[6] = r1[2]; rv[7] = r1[3];
;       } else {
;         const u32x4 rb = *(const u32x4*)xq;
; #pragma unroll
;         for (int e = 0; e < 4; ++e) { rv[2 * e] = bflo(rb[e]); rv[2 * e + 1] = bfhi(rb[e]); }
;       }
;       float o[8]; float ss = 0.f;
; #pragma unroll
;       for (int e = 0; e < 4; ++e) { o[2 * e] = rv[2 * e] + bflo(av[e]); o[2 * e + 1] = rv[2 * e + 1] + bfhi(av[e]); ss += o[2 * e] * o[2 * e] + o[2 * e + 1] * o[2 * e + 1]; }
;       *(u32x4*)xq = (u32x4){pack2(o[0], o[1]), pack2(o[2], o[3]), pack2(o[4], o[5]), pack2(o[6], o[7])};
	v_lshlrev_b32_e32 v4, 16, v120
	v_and_b32_e32 v5, 0xffff0000, v120
	v_lshlrev_b32_e32 v6, 16, v121
	v_and_b32_e32 v7, 0xffff0000, v121
	v_lshlrev_b32_e32 v8, 16, v122
	v_and_b32_e32 v9, 0xffff0000, v122
	v_lshlrev_b32_e32 v10, 16, v123
	v_and_b32_e32 v11, 0xffff0000, v123
	v_add_f32_e32 v80, v80, v4
	v_add_f32_e32 v81, v81, v5
	v_add_f32_e32 v82, v82, v6
	v_add_f32_e32 v83, v83, v7
	v_add_f32_e32 v84, v84, v8
	v_add_f32_e32 v85, v85, v9
	v_add_f32_e32 v86, v86, v10
	v_add_f32_e32 v87, v87, v11
	v_mul_f32_e32 v156, v80, v80
	v_fmac_f32_e32 v156, v81, v81
	v_fmac_f32_e32 v156, v82, v82
	v_fmac_f32_e32 v156, v83, v83
	v_fmac_f32_e32 v156, v84, v84
	v_fmac_f32_e32 v156, v85, v85
	v_fmac_f32_e32 v156, v86, v86
	v_fmac_f32_e32 v156, v87, v87
	v_cvt_pk_bf16_f32 v80, v80, v81
	v_cvt_pk_bf16_f32 v81, v82, v83
	v_cvt_pk_bf16_f32 v82, v84, v85
	v_cvt_pk_bf16_f32 v83, v86, v87
	global_store_dwordx4 v[158:159], v[80:83], off offset:2048
	s_waitcnt vmcnt(7) lgkmcnt(0)
	v_lshlrev_b32_e32 v4, 16, v124
	v_and_b32_e32 v5, 0xffff0000, v124
	v_lshlrev_b32_e32 v6, 16, v125
	v_and_b32_e32 v7, 0xffff0000, v125
	v_lshlrev_b32_e32 v8, 16, v126
	v_and_b32_e32 v9, 0xffff0000, v126
	v_lshlrev_b32_e32 v10, 16, v127
	v_and_b32_e32 v11, 0xffff0000, v127
	v_add_f32_e32 v88, v88, v4
	v_add_f32_e32 v89, v89, v5
	v_add_f32_e32 v90, v90, v6
	v_add_f32_e32 v91, v91, v7
	v_add_f32_e32 v92, v92, v8
	v_add_f32_e32 v93, v93, v9
	v_add_f32_e32 v94, v94, v10
	v_add_f32_e32 v95, v95, v11
	v_mul_f32_e32 v157, v88, v88
	v_fmac_f32_e32 v157, v89, v89
	v_fmac_f32_e32 v157, v90, v90
	v_fmac_f32_e32 v157, v91, v91
	v_fmac_f32_e32 v157, v92, v92
	v_fmac_f32_e32 v157, v93, v93
	v_fmac_f32_e32 v157, v94, v94
	v_fmac_f32_e32 v157, v95, v95
	v_cvt_pk_bf16_f32 v88, v88, v89
	v_cvt_pk_bf16_f32 v89, v90, v91
	v_cvt_pk_bf16_f32 v90, v92, v93
	v_cvt_pk_bf16_f32 v91, v94, v95
	global_store_dwordx4 v[158:159], v[88:91], off offset:3072
; DI void gemm_tile(const Params& p, const GemmJob& j, int mt, int nt, char* smem) {
;     ...
; #pragma unroll
;       for (int d = 1; d < 16; d <<= 1) ss += __shfl_xor(ss, d);
;       if ((tid & 15) == 0 && j.ssq_out) j.ssq_out[(size_t)(t0 + row) * 8 + nt] = ss;
.Lepi_out_sums:
	v_add_f32_dpp v142, v142, v142 quad_perm:[1,0,3,2] row_mask:0xf bank_mask:0xf
	v_add_f32_dpp v143, v143, v143 quad_perm:[1,0,3,2] row_mask:0xf bank_mask:0xf
	v_add_f32_dpp v144, v144, v144 quad_perm:[1,0,3,2] row_mask:0xf bank_mask:0xf
	v_add_f32_dpp v145, v145, v145 quad_perm:[1,0,3,2] row_mask:0xf bank_mask:0xf
	v_add_f32_dpp v146, v146, v146 quad_perm:[1,0,3,2] row_mask:0xf bank_mask:0xf
	v_add_f32_dpp v147, v147, v147 quad_perm:[1,0,3,2] row_mask:0xf bank_mask:0xf
	v_add_f32_dpp v148, v148, v148 quad_perm:[1,0,3,2] row_mask:0xf bank_mask:0xf
	v_add_f32_dpp v149, v149, v149 quad_perm:[1,0,3,2] row_mask:0xf bank_mask:0xf
	v_add_f32_dpp v150, v150, v150 quad_perm:[1,0,3,2] row_mask:0xf bank_mask:0xf
	v_add_f32_dpp v151, v151, v151 quad_perm:[1,0,3,2] row_mask:0xf bank_mask:0xf
	v_add_f32_dpp v152, v152, v152 quad_perm:[1,0,3,2] row_mask:0xf bank_mask:0xf
	v_add_f32_dpp v153, v153, v153 quad_perm:[1,0,3,2] row_mask:0xf bank_mask:0xf
	v_add_f32_dpp v154, v154, v154 quad_perm:[1,0,3,2] row_mask:0xf bank_mask:0xf
	v_add_f32_dpp v155, v155, v155 quad_perm:[1,0,3,2] row_mask:0xf bank_mask:0xf
	v_add_f32_dpp v156, v156, v156 quad_perm:[1,0,3,2] row_mask:0xf bank_mask:0xf
	v_add_f32_dpp v157, v157, v157 quad_perm:[1,0,3,2] row_mask:0xf bank_mask:0xf
	v_add_f32_dpp v142, v142, v142 quad_perm:[2,3,0,1] row_mask:0xf bank_mask:0xf
	v_add_f32_dpp v143, v143, v143 quad_perm:[2,3,0,1] row_mask:0xf bank_mask:0xf
	v_add_f32_dpp v144, v144, v144 quad_perm:[2,3,0,1] row_mask:0xf bank_mask:0xf
	v_add_f32_dpp v145, v145, v145 quad_perm:[2,3,0,1] row_mask:0xf bank_mask:0xf
	v_add_f32_dpp v146, v146, v146 quad_perm:[2,3,0,1] row_mask:0xf bank_mask:0xf
	v_add_f32_dpp v147, v147, v147 quad_perm:[2,3,0,1] row_mask:0xf bank_mask:0xf
	v_add_f32_dpp v148, v148, v148 quad_perm:[2,3,0,1] row_mask:0xf bank_mask:0xf
	v_add_f32_dpp v149, v149, v149 quad_perm:[2,3,0,1] row_mask:0xf bank_mask:0xf
	v_add_f32_dpp v150, v150, v150 quad_perm:[2,3,0,1] row_mask:0xf bank_mask:0xf
	v_add_f32_dpp v151, v151, v151 quad_perm:[2,3,0,1] row_mask:0xf bank_mask:0xf
	v_add_f32_dpp v152, v152, v152 quad_perm:[2,3,0,1] row_mask:0xf bank_mask:0xf
	v_add_f32_dpp v153, v153, v153 quad_perm:[2,3,0,1] row_mask:0xf bank_mask:0xf
	v_add_f32_dpp v154, v154, v154 quad_perm:[2,3,0,1] row_mask:0xf bank_mask:0xf
	v_add_f32_dpp v155, v155, v155 quad_perm:[2,3,0,1] row_mask:0xf bank_mask:0xf
	v_add_f32_dpp v156, v156, v156 quad_perm:[2,3,0,1] row_mask:0xf bank_mask:0xf
	v_add_f32_dpp v157, v157, v157 quad_perm:[2,3,0,1] row_mask:0xf bank_mask:0xf
	v_add_f32_dpp v142, v142, v142 row_half_mirror row_mask:0xf bank_mask:0xf
	v_add_f32_dpp v143, v143, v143 row_half_mirror row_mask:0xf bank_mask:0xf
	v_add_f32_dpp v144, v144, v144 row_half_mirror row_mask:0xf bank_mask:0xf
	v_add_f32_dpp v145, v145, v145 row_half_mirror row_mask:0xf bank_mask:0xf
	v_add_f32_dpp v146, v146, v146 row_half_mirror row_mask:0xf bank_mask:0xf
	v_add_f32_dpp v147, v147, v147 row_half_mirror row_mask:0xf bank_mask:0xf
	v_add_f32_dpp v148, v148, v148 row_half_mirror row_mask:0xf bank_mask:0xf
	v_add_f32_dpp v149, v149, v149 row_half_mirror row_mask:0xf bank_mask:0xf
	v_add_f32_dpp v150, v150, v150 row_half_mirror row_mask:0xf bank_mask:0xf
	v_add_f32_dpp v151, v151, v151 row_half_mirror row_mask:0xf bank_mask:0xf
	v_add_f32_dpp v152, v152, v152 row_half_mirror row_mask:0xf bank_mask:0xf
	v_add_f32_dpp v153, v153, v153 row_half_mirror row_mask:0xf bank_mask:0xf
	v_add_f32_dpp v154, v154, v154 row_half_mirror row_mask:0xf bank_mask:0xf
	v_add_f32_dpp v155, v155, v155 row_half_mirror row_mask:0xf bank_mask:0xf
	v_add_f32_dpp v156, v156, v156 row_half_mirror row_mask:0xf bank_mask:0xf
	v_add_f32_dpp v157, v157, v157 row_half_mirror row_mask:0xf bank_mask:0xf
	v_add_f32_dpp v142, v142, v142 row_mirror row_mask:0xf bank_mask:0xf
	v_add_f32_dpp v143, v143, v143 row_mirror row_mask:0xf bank_mask:0xf
	v_add_f32_dpp v144, v144, v144 row_mirror row_mask:0xf bank_mask:0xf
	v_add_f32_dpp v145, v145, v145 row_mirror row_mask:0xf bank_mask:0xf
	v_add_f32_dpp v146, v146, v146 row_mirror row_mask:0xf bank_mask:0xf
	v_add_f32_dpp v147, v147, v147 row_mirror row_mask:0xf bank_mask:0xf
	v_add_f32_dpp v148, v148, v148 row_mirror row_mask:0xf bank_mask:0xf
	v_add_f32_dpp v149, v149, v149 row_mirror row_mask:0xf bank_mask:0xf
	v_add_f32_dpp v150, v150, v150 row_mirror row_mask:0xf bank_mask:0xf
	v_add_f32_dpp v151, v151, v151 row_mirror row_mask:0xf bank_mask:0xf
	v_add_f32_dpp v152, v152, v152 row_mirror row_mask:0xf bank_mask:0xf
	v_add_f32_dpp v153, v153, v153 row_mirror row_mask:0xf bank_mask:0xf
	v_add_f32_dpp v154, v154, v154 row_mirror row_mask:0xf bank_mask:0xf
	v_add_f32_dpp v155, v155, v155 row_mirror row_mask:0xf bank_mask:0xf
	v_add_f32_dpp v156, v156, v156 row_mirror row_mask:0xf bank_mask:0xf
	v_add_f32_dpp v157, v157, v157 row_mirror row_mask:0xf bank_mask:0xf
	s_and_saveexec_b64 s[62:63], s[10:11]
	s_cbranch_execz .Lepi_out_done
	v_lshlrev_b64 v[4:5], 5, v[20:21]
	v_lshl_add_u64 v[4:5], s[54:55], 0, v[4:5]
	s_mov_b64 s[6:7], 0x1000
	v_lshl_add_u64 v[6:7], v[4:5], 0, s[6:7]
	global_store_dword v[4:5], v142, off
	global_store_dword v[4:5], v143, off offset:512
	global_store_dword v[4:5], v144, off offset:1024
	global_store_dword v[4:5], v145, off offset:1536
	global_store_dword v[4:5], v146, off offset:2048
	global_store_dword v[4:5], v147, off offset:2560
	global_store_dword v[4:5], v148, off offset:3072
	global_store_dword v[4:5], v149, off offset:3584
	global_store_dword v[6:7], v150, off
	global_store_dword v[6:7], v151, off offset:512
	global_store_dword v[6:7], v152, off offset:1024
	global_store_dword v[6:7], v153, off offset:1536
	global_store_dword v[6:7], v154, off offset:2048
	global_store_dword v[6:7], v155, off offset:2560
	global_store_dword v[6:7], v156, off offset:3072
	global_store_dword v[6:7], v157, off offset:3584
.Lepi_out_done:
	s_or_b64 exec, exec, s[62:63]
	s_movk_i32 s58, 0x1000
	s_branch .LBB0_884

; DI float bflo(unsigned v) { return __uint_as_float(v << 16); }
; DI float bfhi(unsigned v) { return __uint_as_float(v & 0xffff0000u); }
; DI int otid() { int t = threadIdx.x; asm volatile("" : "+v"(t)); return t; }
; DI size_t blk(size_t row, int k, int R) { return ((size_t)(k >> 5) * R + row) * 32 + (k & 31); }
; DI void final_norm_phase(const Params& p) {
;   const int tid = otid(), lane = tid & 63; const int wv = blockIdx.x * 4 + (tid >> 6), nw = gridDim.x * 4;
;   for (int t = wv; t < NTOK; t += nw) {
;     const bf16_t* src = p.xb + blk(t, lane * 16, NTOK);
;     const u32x4 a = *(const u32x4*)src, b = *(const u32x4*)(src + 8);
;     float v[16]; float ss = 0.f;
; #pragma unroll
;     for (int e = 0; e < 4; ++e) { v[2 * e] = bflo(a[e]); v[2 * e + 1] = bfhi(a[e]); v[8 + 2 * e] = bflo(b[e]); v[8 + 2 * e + 1] = bfhi(b[e]); }
; #pragma unroll
;     for (int i = 0; i < 16; ++i) ss += v[i] * v[i];
; #pragma unroll
;     for (int d = 1; d < 64; d <<= 1) ss += __shfl_xor(ss, d);
;     const float rs = rsqrtf(ss * (1.f / 1024.f) + 1e-6f);
;     float* row = p.out + (size_t)t * 1024 + lane * 16;
; #pragma unroll
;     for (int i = 0; i < 4; ++i) {
;       const f32x4 gn = *(const f32x4*)(p.final_norm + lane * 16 + 4 * i);
;       f32x4 o; o[0] = v[4 * i] * rs * gn[0]; o[1] = v[4 * i + 1] * rs * gn[1]; o[2] = v[4 * i + 2] * rs * gn[2]; o[3] = v[4 * i + 3] * rs * gn[3];
;       *(f32x4*)(row + 4 * i) = o;
;     }
.LBB0_1055:
	v_readlane_b32 s0, v230, 34
	s_load_dwordx2 s[10:11], s[80:81], 0xf8
	s_load_dwordx4 s[4:7], s[80:81], 0x60
	v_lshrrev_b32_e32 v0, 6, v167
	v_and_b32_e32 v1, 63, v167
	s_lshl_b32 s2, s82, 2
	v_readfirstlane_b32 s1, v0
	s_movk_i32 s8, 0x7fff
	s_mov_b32 s13, 0
	s_mov_b32 s3, 0x800000
	s_nop 1
	s_add_i32 s9, s0, s1
	s_cmp_gt_i32 s9, s8
	s_cbranch_scc1 .Lfin_done
	s_mov_b32 s20, s9
	v_lshlrev_b32_e32 v2, 6, v1
	v_lshrrev_b32_e32 v3, 1, v1
	v_lshlrev_b32_e32 v3, 21, v3
	v_and_b32_e32 v4, 1, v1
	v_lshl_or_b32 v4, v4, 5, v3
	v_mov_b32_e32 v5, 0
	v_mov_b32_e32 v3, 0
	v_mov_b32_e32 v12, 0x358637bd
	s_waitcnt lgkmcnt(0)
	v_lshl_add_u64 v[4:5], s[10:11], 0, v[4:5]
	v_lshl_add_u64 v[6:7], s[4:5], 0, v[2:3]
	v_lshl_add_u64 v[8:9], s[6:7], 0, v[2:3]
	global_load_dwordx4 v[50:53], v[6:7], off
	global_load_dwordx4 v[54:57], v[6:7], off offset:16
	global_load_dwordx4 v[58:61], v[6:7], off offset:32
	global_load_dwordx4 v[62:65], v[6:7], off offset:48
	s_min_i32 s12, s20, s8
	s_lshl_b64 s[14:15], s[12:13], 6
	s_add_i32 s20, s20, s2
	v_lshl_add_u64 v[10:11], s[14:15], 0, v[4:5]
	global_load_dwordx4 v[66:69], v[10:11], off
	global_load_dwordx4 v[70:73], v[10:11], off offset:16
	s_min_i32 s12, s20, s8
	s_lshl_b64 s[14:15], s[12:13], 6
	s_add_i32 s20, s20, s2
	v_lshl_add_u64 v[10:11], s[14:15], 0, v[4:5]
	global_load_dwordx4 v[74:77], v[10:11], off
	global_load_dwordx4 v[78:81], v[10:11], off offset:16
	s_min_i32 s12, s20, s8
	s_lshl_b64 s[14:15], s[12:13], 6
	s_add_i32 s20, s20, s2
	v_lshl_add_u64 v[10:11], s[14:15], 0, v[4:5]
	global_load_dwordx4 v[82:85], v[10:11], off
	global_load_dwordx4 v[86:89], v[10:11], off offset:16
	s_min_i32 s12, s20, s8
	s_lshl_b64 s[14:15], s[12:13], 6
	s_add_i32 s20, s20, s2
	v_lshl_add_u64 v[10:11], s[14:15], 0, v[4:5]
	global_load_dwordx4 v[90:93], v[10:11], off
	global_load_dwordx4 v[94:97], v[10:11], off offset:16
	s_min_i32 s12, s20, s8
	s_lshl_b64 s[14:15], s[12:13], 6
	s_add_i32 s20, s20, s2
	v_lshl_add_u64 v[10:11], s[14:15], 0, v[4:5]
	global_load_dwordx4 v[98:101], v[10:11], off
	global_load_dwordx4 v[102:105], v[10:11], off offset:16
	s_min_i32 s12, s20, s8
	s_lshl_b64 s[14:15], s[12:13], 6
	s_add_i32 s20, s20, s2
	v_lshl_add_u64 v[10:11], s[14:15], 0, v[4:5]
	global_load_dwordx4 v[106:109], v[10:11], off
	global_load_dwordx4 v[110:113], v[10:11], off offset:16
	s_min_i32 s12, s20, s8
	s_lshl_b64 s[14:15], s[12:13], 6
	s_add_i32 s20, s20, s2
	v_lshl_add_u64 v[10:11], s[14:15], 0, v[4:5]
	global_load_dwordx4 v[114:117], v[10:11], off
	global_load_dwordx4 v[118:121], v[10:11], off offset:16
	s_min_i32 s12, s20, s8
	s_lshl_b64 s[14:15], s[12:13], 6
	s_add_i32 s20, s20, s2
	v_lshl_add_u64 v[10:11], s[14:15], 0, v[4:5]
	global_load_dwordx4 v[122:125], v[10:11], off
	global_load_dwordx4 v[126:129], v[10:11], off offset:16
	s_waitcnt vmcnt(8)
.Lfin_loop:
	s_cmp_gt_i32 s9, s8
	s_cbranch_scc1 .Lfin_done
	v_lshlrev_b32_e32 v20, 16, v66
	v_and_b32_e32 v21, 0xffff0000, v66
	v_lshlrev_b32_e32 v22, 16, v67
	v_and_b32_e32 v23, 0xffff0000, v67
	v_lshlrev_b32_e32 v24, 16, v68
	v_and_b32_e32 v25, 0xffff0000, v68
	v_lshlrev_b32_e32 v26, 16, v69
	v_and_b32_e32 v27, 0xffff0000, v69
	v_lshlrev_b32_e32 v28, 16, v70
	v_and_b32_e32 v29, 0xffff0000, v70
	v_lshlrev_b32_e32 v30, 16, v71
	v_and_b32_e32 v31, 0xffff0000, v71
	v_lshlrev_b32_e32 v32, 16, v72
	v_and_b32_e32 v33, 0xffff0000, v72
	v_lshlrev_b32_e32 v34, 16, v73
	v_and_b32_e32 v35, 0xffff0000, v73
	v_mul_f32_e32 v36, v20, v20
	v_fmac_f32_e32 v36, v21, v21
	v_fmac_f32_e32 v36, v22, v22
	v_fmac_f32_e32 v36, v23, v23
	v_fmac_f32_e32 v36, v24, v24
	v_fmac_f32_e32 v36, v25, v25
	v_fmac_f32_e32 v36, v26, v26
	v_fmac_f32_e32 v36, v27, v27
	v_fmac_f32_e32 v36, v28, v28
	v_fmac_f32_e32 v36, v29, v29
	v_fmac_f32_e32 v36, v30, v30
	v_fmac_f32_e32 v36, v31, v31
	v_fmac_f32_e32 v36, v32, v32
	v_fmac_f32_e32 v36, v33, v33
	v_fmac_f32_e32 v36, v34, v34
	v_fmac_f32_e32 v36, v35, v35
	s_mov_b32 s12, s9
	s_lshl_b64 s[14:15], s[12:13], 12
	s_add_i32 s9, s9, s2
	v_add_f32_dpp v36, v36, v36 quad_perm:[1,0,3,2] row_mask:0xf bank_mask:0xf
	v_lshl_add_u64 v[10:11], s[14:15], 0, v[8:9]
	s_nop 0
	v_add_f32_dpp v36, v36, v36 quad_perm:[2,3,0,1] row_mask:0xf bank_mask:0xf
	v_lshl_add_u64 v[10:11], s[14:15], 0, v[8:9]
	s_nop 0
	v_add_f32_dpp v36, v36, v36 row_half_mirror row_mask:0xf bank_mask:0xf
	v_lshl_add_u64 v[10:11], s[14:15], 0, v[8:9]
	s_nop 0
	v_add_f32_dpp v36, v36, v36 row_mirror row_mask:0xf bank_mask:0xf
	v_lshl_add_u64 v[10:11], s[14:15], 0, v[8:9]
	s_nop 0
	v_readlane_b32 s16, v36, 0
	v_readlane_b32 s17, v36, 16
	v_readlane_b32 s18, v36, 32
	v_readlane_b32 s19, v36, 48
	s_nop 1
	v_mov_b32_e32 v37, s16
	v_add_f32_e32 v37, s17, v37
	v_add_f32_e32 v37, s18, v37
	v_add_f32_e32 v37, s19, v37
	v_fmamk_f32 v37, v37, 0x3a800000, v12
	v_mul_f32_e32 v38, 0x4b800000, v37
	v_cmp_gt_f32_e32 vcc, s3, v37
	s_nop 1
	v_cndmask_b32_e32 v37, v37, v38, vcc
	v_rsq_f32_e32 v37, v37
	s_nop 0
	v_mul_f32_e32 v38, 0x45800000, v37
	v_cndmask_b32_e32 v37, v37, v38, vcc
	v_mul_f32_e32 v20, v20, v37
	v_mul_f32_e32 v21, v21, v37
	v_mul_f32_e32 v22, v22, v37
	v_mul_f32_e32 v23, v23, v37
	v_mul_f32_e32 v24, v24, v37
	v_mul_f32_e32 v25, v25, v37
	v_mul_f32_e32 v26, v26, v37
	v_mul_f32_e32 v27, v27, v37
	v_mul_f32_e32 v28, v28, v37
	v_mul_f32_e32 v29, v29, v37
	v_mul_f32_e32 v30, v30, v37
	v_mul_f32_e32 v31, v31, v37
	v_mul_f32_e32 v32, v32, v37
	v_mul_f32_e32 v33, v33, v37
	v_mul_f32_e32 v34, v34, v37
	v_mul_f32_e32 v35, v35, v37
	v_mul_f32_e32 v20, v20, v50
	v_mul_f32_e32 v21, v21, v51
	v_mul_f32_e32 v22, v22, v52
	v_mul_f32_e32 v23, v23, v53
	v_mul_f32_e32 v24, v24, v54
	v_mul_f32_e32 v25, v25, v55
	v_mul_f32_e32 v26, v26, v56
	v_mul_f32_e32 v27, v27, v57
	v_mul_f32_e32 v28, v28, v58
	v_mul_f32_e32 v29, v29, v59
	v_mul_f32_e32 v30, v30, v60
	v_mul_f32_e32 v31, v31, v61
	v_mul_f32_e32 v32, v32, v62
	v_mul_f32_e32 v33, v33, v63
	v_mul_f32_e32 v34, v34, v64
	v_mul_f32_e32 v35, v35, v65
	global_store_dwordx4 v[10:11], v[20:23], off
	global_store_dwordx4 v[10:11], v[24:27], off offset:16
	global_store_dwordx4 v[10:11], v[28:31], off offset:32
	global_store_dwordx4 v[10:11], v[32:35], off offset:48
	s_cmp_gt_i32 s9, s8
	s_cbranch_scc1 .Lfin_done
; DI float bflo(unsigned v) { return __uint_as_float(v << 16); }
; DI float bfhi(unsigned v) { return __uint_as_float(v & 0xffff0000u); }
; DI size_t blk(size_t row, int k, int R) { return ((size_t)(k >> 5) * R + row) * 32 + (k & 31); }
; DI void final_norm_phase(const Params& p) {
;     ...
;   for (int t = wv; t < NTOK; t += nw) {
;     const bf16_t* src = p.xb + blk(t, lane * 16, NTOK);
;     const u32x4 a = *(const u32x4*)src, b = *(const u32x4*)(src + 8);
;     float v[16]; float ss = 0.f;
; #pragma unroll
;     for (int e = 0; e < 4; ++e) { v[2 * e] = bflo(a[e]); v[2 * e + 1] = bfhi(a[e]); v[8 + 2 * e] = bflo(b[e]); v[8 + 2 * e + 1] = bfhi(b[e]); }
; #pragma unroll
;     for (int i = 0; i < 16; ++i) ss += v[i] * v[i];
; #pragma unroll
;     for (int d = 1; d < 64; d <<= 1) ss += __shfl_xor(ss, d);
;     const float rs = rsqrtf(ss * (1.f / 1024.f) + 1e-6f);
;     float* row = p.out + (size_t)t * 1024 + lane * 16;
; #pragma unroll
;     for (int i = 0; i < 4; ++i) {
;       const f32x4 gn = *(const f32x4*)(p.final_norm + lane * 16 + 4 * i);
;       f32x4 o; o[0] = v[4 * i] * rs * gn[0]; o[1] = v[4 * i + 1] * rs * gn[1]; o[2] = v[4 * i + 2] * rs * gn[2]; o[3] = v[4 * i + 3] * rs * gn[3];
;       *(f32x4*)(row + 4 * i) = o;
;     }
	v_lshlrev_b32_e32 v20, 16, v74
	v_and_b32_e32 v21, 0xffff0000, v74
	v_lshlrev_b32_e32 v22, 16, v75
	v_and_b32_e32 v23, 0xffff0000, v75
	v_lshlrev_b32_e32 v24, 16, v76
	v_and_b32_e32 v25, 0xffff0000, v76
	v_lshlrev_b32_e32 v26, 16, v77
	v_and_b32_e32 v27, 0xffff0000, v77
	v_lshlrev_b32_e32 v28, 16, v78
	v_and_b32_e32 v29, 0xffff0000, v78
	v_lshlrev_b32_e32 v30, 16, v79
	v_and_b32_e32 v31, 0xffff0000, v79
	v_lshlrev_b32_e32 v32, 16, v80
	v_and_b32_e32 v33, 0xffff0000, v80
	v_lshlrev_b32_e32 v34, 16, v81
	v_and_b32_e32 v35, 0xffff0000, v81
	v_mul_f32_e32 v36, v20, v20
	v_fmac_f32_e32 v36, v21, v21
	v_fmac_f32_e32 v36, v22, v22
	v_fmac_f32_e32 v36, v23, v23
	v_fmac_f32_e32 v36, v24, v24
	v_fmac_f32_e32 v36, v25, v25
	v_fmac_f32_e32 v36, v26, v26
	v_fmac_f32_e32 v36, v27, v27
	v_fmac_f32_e32 v36, v28, v28
	v_fmac_f32_e32 v36, v29, v29
	v_fmac_f32_e32 v36, v30, v30
	v_fmac_f32_e32 v36, v31, v31
	v_fmac_f32_e32 v36, v32, v32
	v_fmac_f32_e32 v36, v33, v33
	v_fmac_f32_e32 v36, v34, v34
	v_fmac_f32_e32 v36, v35, v35
	s_mov_b32 s12, s9
	s_lshl_b64 s[14:15], s[12:13], 12
	s_add_i32 s9, s9, s2
	v_add_f32_dpp v36, v36, v36 quad_perm:[1,0,3,2] row_mask:0xf bank_mask:0xf
	v_lshl_add_u64 v[10:11], s[14:15], 0, v[8:9]
	s_nop 0
	v_add_f32_dpp v36, v36, v36 quad_perm:[2,3,0,1] row_mask:0xf bank_mask:0xf
	v_lshl_add_u64 v[10:11], s[14:15], 0, v[8:9]
	s_nop 0
	v_add_f32_dpp v36, v36, v36 row_half_mirror row_mask:0xf bank_mask:0xf
	v_lshl_add_u64 v[10:11], s[14:15], 0, v[8:9]
	s_nop 0
	v_add_f32_dpp v36, v36, v36 row_mirror row_mask:0xf bank_mask:0xf
	v_lshl_add_u64 v[10:11], s[14:15], 0, v[8:9]
	s_nop 0
	v_readlane_b32 s16, v36, 0
	v_readlane_b32 s17, v36, 16
	v_readlane_b32 s18, v36, 32
	v_readlane_b32 s19, v36, 48
	s_nop 1
	v_mov_b32_e32 v37, s16
	v_add_f32_e32 v37, s17, v37
	v_add_f32_e32 v37, s18, v37
	v_add_f32_e32 v37, s19, v37
	v_fmamk_f32 v37, v37, 0x3a800000, v12
	v_mul_f32_e32 v38, 0x4b800000, v37
	v_cmp_gt_f32_e32 vcc, s3, v37
	s_nop 1
	v_cndmask_b32_e32 v37, v37, v38, vcc
	v_rsq_f32_e32 v37, v37
	s_nop 0
	v_mul_f32_e32 v38, 0x45800000, v37
	v_cndmask_b32_e32 v37, v37, v38, vcc
	v_mul_f32_e32 v20, v20, v37
	v_mul_f32_e32 v21, v21, v37
	v_mul_f32_e32 v22, v22, v37
	v_mul_f32_e32 v23, v23, v37
	v_mul_f32_e32 v24, v24, v37
	v_mul_f32_e32 v25, v25, v37
	v_mul_f32_e32 v26, v26, v37
	v_mul_f32_e32 v27, v27, v37
	v_mul_f32_e32 v28, v28, v37
	v_mul_f32_e32 v29, v29, v37
	v_mul_f32_e32 v30, v30, v37
	v_mul_f32_e32 v31, v31, v37
	v_mul_f32_e32 v32, v32, v37
	v_mul_f32_e32 v33, v33, v37
	v_mul_f32_e32 v34, v34, v37
	v_mul_f32_e32 v35, v35, v37
	v_mul_f32_e32 v20, v20, v50
	v_mul_f32_e32 v21, v21, v51
	v_mul_f32_e32 v22, v22, v52
	v_mul_f32_e32 v23, v23, v53
	v_mul_f32_e32 v24, v24, v54
	v_mul_f32_e32 v25, v25, v55
	v_mul_f32_e32 v26, v26, v56
	v_mul_f32_e32 v27, v27, v57
	v_mul_f32_e32 v28, v28, v58
	v_mul_f32_e32 v29, v29, v59
	v_mul_f32_e32 v30, v30, v60
	v_mul_f32_e32 v31, v31, v61
	v_mul_f32_e32 v32, v32, v62
	v_mul_f32_e32 v33, v33, v63
	v_mul_f32_e32 v34, v34, v64
	v_mul_f32_e32 v35, v35, v65
	global_store_dwordx4 v[10:11], v[20:23], off
	global_store_dwordx4 v[10:11], v[24:27], off offset:16
	global_store_dwordx4 v[10:11], v[28:31], off offset:32
	global_store_dwordx4 v[10:11], v[32:35], off offset:48
	s_cmp_gt_i32 s9, s8
	s_cbranch_scc1 .Lfin_done
	v_lshlrev_b32_e32 v20, 16, v82
	v_and_b32_e32 v21, 0xffff0000, v82
	v_lshlrev_b32_e32 v22, 16, v83
	v_and_b32_e32 v23, 0xffff0000, v83
	v_lshlrev_b32_e32 v24, 16, v84
	v_and_b32_e32 v25, 0xffff0000, v84
	v_lshlrev_b32_e32 v26, 16, v85
	v_and_b32_e32 v27, 0xffff0000, v85
	v_lshlrev_b32_e32 v28, 16, v86
	v_and_b32_e32 v29, 0xffff0000, v86
	v_lshlrev_b32_e32 v30, 16, v87
	v_and_b32_e32 v31, 0xffff0000, v87
	v_lshlrev_b32_e32 v32, 16, v88
	v_and_b32_e32 v33, 0xffff0000, v88
	v_lshlrev_b32_e32 v34, 16, v89
	v_and_b32_e32 v35, 0xffff0000, v89
	v_mul_f32_e32 v36, v20, v20
	v_fmac_f32_e32 v36, v21, v21
	v_fmac_f32_e32 v36, v22, v22
	v_fmac_f32_e32 v36, v23, v23
	v_fmac_f32_e32 v36, v24, v24
	v_fmac_f32_e32 v36, v25, v25
	v_fmac_f32_e32 v36, v26, v26
	v_fmac_f32_e32 v36, v27, v27
	v_fmac_f32_e32 v36, v28, v28
	v_fmac_f32_e32 v36, v29, v29
	v_fmac_f32_e32 v36, v30, v30
	v_fmac_f32_e32 v36, v31, v31
	v_fmac_f32_e32 v36, v32, v32
	v_fmac_f32_e32 v36, v33, v33
	v_fmac_f32_e32 v36, v34, v34
	v_fmac_f32_e32 v36, v35, v35
	s_mov_b32 s12, s9
	s_lshl_b64 s[14:15], s[12:13], 12
	s_add_i32 s9, s9, s2
	v_add_f32_dpp v36, v36, v36 quad_perm:[1,0,3,2] row_mask:0xf bank_mask:0xf
	v_lshl_add_u64 v[10:11], s[14:15], 0, v[8:9]
	s_nop 0
	v_add_f32_dpp v36, v36, v36 quad_perm:[2,3,0,1] row_mask:0xf bank_mask:0xf
	v_lshl_add_u64 v[10:11], s[14:15], 0, v[8:9]
	s_nop 0
	v_add_f32_dpp v36, v36, v36 row_half_mirror row_mask:0xf bank_mask:0xf
	v_lshl_add_u64 v[10:11], s[14:15], 0, v[8:9]
	s_nop 0
	v_add_f32_dpp v36, v36, v36 row_mirror row_mask:0xf bank_mask:0xf
	v_lshl_add_u64 v[10:11], s[14:15], 0, v[8:9]
	s_nop 0
	v_readlane_b32 s16, v36, 0
	v_readlane_b32 s17, v36, 16
	v_readlane_b32 s18, v36, 32
	v_readlane_b32 s19, v36, 48
	s_nop 1
	v_mov_b32_e32 v37, s16
	v_add_f32_e32 v37, s17, v37
	v_add_f32_e32 v37, s18, v37
	v_add_f32_e32 v37, s19, v37
	v_fmamk_f32 v37, v37, 0x3a800000, v12
	v_mul_f32_e32 v38, 0x4b800000, v37
	v_cmp_gt_f32_e32 vcc, s3, v37
	s_nop 1
	v_cndmask_b32_e32 v37, v37, v38, vcc
	v_rsq_f32_e32 v37, v37
	s_nop 0
	v_mul_f32_e32 v38, 0x45800000, v37
	v_cndmask_b32_e32 v37, v37, v38, vcc
	v_mul_f32_e32 v20, v20, v37
	v_mul_f32_e32 v21, v21, v37
	v_mul_f32_e32 v22, v22, v37
	v_mul_f32_e32 v23, v23, v37
	v_mul_f32_e32 v24, v24, v37
	v_mul_f32_e32 v25, v25, v37
	v_mul_f32_e32 v26, v26, v37
	v_mul_f32_e32 v27, v27, v37
	v_mul_f32_e32 v28, v28, v37
	v_mul_f32_e32 v29, v29, v37
	v_mul_f32_e32 v30, v30, v37
	v_mul_f32_e32 v31, v31, v37
	v_mul_f32_e32 v32, v32, v37
	v_mul_f32_e32 v33, v33, v37
	v_mul_f32_e32 v34, v34, v37
	v_mul_f32_e32 v35, v35, v37
	v_mul_f32_e32 v20, v20, v50
	v_mul_f32_e32 v21, v21, v51
	v_mul_f32_e32 v22, v22, v52
	v_mul_f32_e32 v23, v23, v53
	v_mul_f32_e32 v24, v24, v54
	v_mul_f32_e32 v25, v25, v55
	v_mul_f32_e32 v26, v26, v56
	v_mul_f32_e32 v27, v27, v57
	v_mul_f32_e32 v28, v28, v58
	v_mul_f32_e32 v29, v29, v59
	v_mul_f32_e32 v30, v30, v60
	v_mul_f32_e32 v31, v31, v61
	v_mul_f32_e32 v32, v32, v62
	v_mul_f32_e32 v33, v33, v63
	v_mul_f32_e32 v34, v34, v64
	v_mul_f32_e32 v35, v35, v65
	global_store_dwordx4 v[10:11], v[20:23], off
	global_store_dwordx4 v[10:11], v[24:27], off offset:16
	global_store_dwordx4 v[10:11], v[28:31], off offset:32
	global_store_dwordx4 v[10:11], v[32:35], off offset:48
	s_cmp_gt_i32 s9, s8
	s_cbranch_scc1 .Lfin_done
; DI float bflo(unsigned v) { return __uint_as_float(v << 16); }
; DI float bfhi(unsigned v) { return __uint_as_float(v & 0xffff0000u); }
; DI size_t blk(size_t row, int k, int R) { return ((size_t)(k >> 5) * R + row) * 32 + (k & 31); }
; DI void final_norm_phase(const Params& p) {
;     ...
;   for (int t = wv; t < NTOK; t += nw) {
;     const bf16_t* src = p.xb + blk(t, lane * 16, NTOK);
;     const u32x4 a = *(const u32x4*)src, b = *(const u32x4*)(src + 8);
;     float v[16]; float ss = 0.f;
; #pragma unroll
;     for (int e = 0; e < 4; ++e) { v[2 * e] = bflo(a[e]); v[2 * e + 1] = bfhi(a[e]); v[8 + 2 * e] = bflo(b[e]); v[8 + 2 * e + 1] = bfhi(b[e]); }
; #pragma unroll
;     for (int i = 0; i < 16; ++i) ss += v[i] * v[i];
; #pragma unroll
;     for (int d = 1; d < 64; d <<= 1) ss += __shfl_xor(ss, d);
;     const float rs = rsqrtf(ss * (1.f / 1024.f) + 1e-6f);
;     float* row = p.out + (size_t)t * 1024 + lane * 16;
; #pragma unroll
;     for (int i = 0; i < 4; ++i) {
;       const f32x4 gn = *(const f32x4*)(p.final_norm + lane * 16 + 4 * i);
;       f32x4 o; o[0] = v[4 * i] * rs * gn[0]; o[1] = v[4 * i + 1] * rs * gn[1]; o[2] = v[4 * i + 2] * rs * gn[2]; o[3] = v[4 * i + 3] * rs * gn[3];
;       *(f32x4*)(row + 4 * i) = o;
;     }
	v_lshlrev_b32_e32 v20, 16, v90
	v_and_b32_e32 v21, 0xffff0000, v90
	v_lshlrev_b32_e32 v22, 16, v91
	v_and_b32_e32 v23, 0xffff0000, v91
	v_lshlrev_b32_e32 v24, 16, v92
	v_and_b32_e32 v25, 0xffff0000, v92
	v_lshlrev_b32_e32 v26, 16, v93
	v_and_b32_e32 v27, 0xffff0000, v93
	v_lshlrev_b32_e32 v28, 16, v94
	v_and_b32_e32 v29, 0xffff0000, v94
	v_lshlrev_b32_e32 v30, 16, v95
	v_and_b32_e32 v31, 0xffff0000, v95
	v_lshlrev_b32_e32 v32, 16, v96
	v_and_b32_e32 v33, 0xffff0000, v96
	v_lshlrev_b32_e32 v34, 16, v97
	v_and_b32_e32 v35, 0xffff0000, v97
	v_mul_f32_e32 v36, v20, v20
	v_fmac_f32_e32 v36, v21, v21
	v_fmac_f32_e32 v36, v22, v22
	v_fmac_f32_e32 v36, v23, v23
	v_fmac_f32_e32 v36, v24, v24
	v_fmac_f32_e32 v36, v25, v25
	v_fmac_f32_e32 v36, v26, v26
	v_fmac_f32_e32 v36, v27, v27
	v_fmac_f32_e32 v36, v28, v28
	v_fmac_f32_e32 v36, v29, v29
	v_fmac_f32_e32 v36, v30, v30
	v_fmac_f32_e32 v36, v31, v31
	v_fmac_f32_e32 v36, v32, v32
	v_fmac_f32_e32 v36, v33, v33
	v_fmac_f32_e32 v36, v34, v34
	v_fmac_f32_e32 v36, v35, v35
	s_mov_b32 s12, s9
	s_lshl_b64 s[14:15], s[12:13], 12
	s_add_i32 s9, s9, s2
	v_add_f32_dpp v36, v36, v36 quad_perm:[1,0,3,2] row_mask:0xf bank_mask:0xf
	v_lshl_add_u64 v[10:11], s[14:15], 0, v[8:9]
	s_nop 0
	v_add_f32_dpp v36, v36, v36 quad_perm:[2,3,0,1] row_mask:0xf bank_mask:0xf
	v_lshl_add_u64 v[10:11], s[14:15], 0, v[8:9]
	s_nop 0
	v_add_f32_dpp v36, v36, v36 row_half_mirror row_mask:0xf bank_mask:0xf
	v_lshl_add_u64 v[10:11], s[14:15], 0, v[8:9]
	s_nop 0
	v_add_f32_dpp v36, v36, v36 row_mirror row_mask:0xf bank_mask:0xf
	v_lshl_add_u64 v[10:11], s[14:15], 0, v[8:9]
	s_nop 0
	v_readlane_b32 s16, v36, 0
	v_readlane_b32 s17, v36, 16
	v_readlane_b32 s18, v36, 32
	v_readlane_b32 s19, v36, 48
	s_nop 1
	v_mov_b32_e32 v37, s16
	v_add_f32_e32 v37, s17, v37
	v_add_f32_e32 v37, s18, v37
	v_add_f32_e32 v37, s19, v37
	v_fmamk_f32 v37, v37, 0x3a800000, v12
	v_mul_f32_e32 v38, 0x4b800000, v37
	v_cmp_gt_f32_e32 vcc, s3, v37
	s_nop 1
	v_cndmask_b32_e32 v37, v37, v38, vcc
	v_rsq_f32_e32 v37, v37
	s_nop 0
	v_mul_f32_e32 v38, 0x45800000, v37
	v_cndmask_b32_e32 v37, v37, v38, vcc
	v_mul_f32_e32 v20, v20, v37
	v_mul_f32_e32 v21, v21, v37
	v_mul_f32_e32 v22, v22, v37
	v_mul_f32_e32 v23, v23, v37
	v_mul_f32_e32 v24, v24, v37
	v_mul_f32_e32 v25, v25, v37
	v_mul_f32_e32 v26, v26, v37
	v_mul_f32_e32 v27, v27, v37
	v_mul_f32_e32 v28, v28, v37
	v_mul_f32_e32 v29, v29, v37
	v_mul_f32_e32 v30, v30, v37
	v_mul_f32_e32 v31, v31, v37
	v_mul_f32_e32 v32, v32, v37
	v_mul_f32_e32 v33, v33, v37
	v_mul_f32_e32 v34, v34, v37
	v_mul_f32_e32 v35, v35, v37
	v_mul_f32_e32 v20, v20, v50
	v_mul_f32_e32 v21, v21, v51
	v_mul_f32_e32 v22, v22, v52
	v_mul_f32_e32 v23, v23, v53
	v_mul_f32_e32 v24, v24, v54
	v_mul_f32_e32 v25, v25, v55
	v_mul_f32_e32 v26, v26, v56
	v_mul_f32_e32 v27, v27, v57
	v_mul_f32_e32 v28, v28, v58
	v_mul_f32_e32 v29, v29, v59
	v_mul_f32_e32 v30, v30, v60
	v_mul_f32_e32 v31, v31, v61
	v_mul_f32_e32 v32, v32, v62
	v_mul_f32_e32 v33, v33, v63
	v_mul_f32_e32 v34, v34, v64
	v_mul_f32_e32 v35, v35, v65
	global_store_dwordx4 v[10:11], v[20:23], off
	global_store_dwordx4 v[10:11], v[24:27], off offset:16
	global_store_dwordx4 v[10:11], v[28:31], off offset:32
	global_store_dwordx4 v[10:11], v[32:35], off offset:48
	s_min_i32 s12, s20, s8
	s_lshl_b64 s[14:15], s[12:13], 6
	s_add_i32 s20, s20, s2
	v_lshl_add_u64 v[10:11], s[14:15], 0, v[4:5]
	global_load_dwordx4 v[66:69], v[10:11], off
	global_load_dwordx4 v[70:73], v[10:11], off offset:16
	s_min_i32 s12, s20, s8
	s_lshl_b64 s[14:15], s[12:13], 6
	s_add_i32 s20, s20, s2
	v_lshl_add_u64 v[10:11], s[14:15], 0, v[4:5]
	global_load_dwordx4 v[74:77], v[10:11], off
	global_load_dwordx4 v[78:81], v[10:11], off offset:16
	s_min_i32 s12, s20, s8
	s_lshl_b64 s[14:15], s[12:13], 6
	s_add_i32 s20, s20, s2
	v_lshl_add_u64 v[10:11], s[14:15], 0, v[4:5]
	global_load_dwordx4 v[82:85], v[10:11], off
	global_load_dwordx4 v[86:89], v[10:11], off offset:16
	s_min_i32 s12, s20, s8
	s_lshl_b64 s[14:15], s[12:13], 6
	s_add_i32 s20, s20, s2
	v_lshl_add_u64 v[10:11], s[14:15], 0, v[4:5]
	global_load_dwordx4 v[90:93], v[10:11], off
	global_load_dwordx4 v[94:97], v[10:11], off offset:16
	s_waitcnt vmcnt(24)
	s_cmp_gt_i32 s9, s8
	s_cbranch_scc1 .Lfin_done
	v_lshlrev_b32_e32 v20, 16, v98
	v_and_b32_e32 v21, 0xffff0000, v98
	v_lshlrev_b32_e32 v22, 16, v99
	v_and_b32_e32 v23, 0xffff0000, v99
	v_lshlrev_b32_e32 v24, 16, v100
	v_and_b32_e32 v25, 0xffff0000, v100
	v_lshlrev_b32_e32 v26, 16, v101
	v_and_b32_e32 v27, 0xffff0000, v101
	v_lshlrev_b32_e32 v28, 16, v102
	v_and_b32_e32 v29, 0xffff0000, v102
	v_lshlrev_b32_e32 v30, 16, v103
	v_and_b32_e32 v31, 0xffff0000, v103
	v_lshlrev_b32_e32 v32, 16, v104
	v_and_b32_e32 v33, 0xffff0000, v104
	v_lshlrev_b32_e32 v34, 16, v105
	v_and_b32_e32 v35, 0xffff0000, v105
	v_mul_f32_e32 v36, v20, v20
	v_fmac_f32_e32 v36, v21, v21
	v_fmac_f32_e32 v36, v22, v22
	v_fmac_f32_e32 v36, v23, v23
	v_fmac_f32_e32 v36, v24, v24
	v_fmac_f32_e32 v36, v25, v25
	v_fmac_f32_e32 v36, v26, v26
	v_fmac_f32_e32 v36, v27, v27
	v_fmac_f32_e32 v36, v28, v28
	v_fmac_f32_e32 v36, v29, v29
	v_fmac_f32_e32 v36, v30, v30
	v_fmac_f32_e32 v36, v31, v31
	v_fmac_f32_e32 v36, v32, v32
	v_fmac_f32_e32 v36, v33, v33
	v_fmac_f32_e32 v36, v34, v34
	v_fmac_f32_e32 v36, v35, v35
	s_mov_b32 s12, s9
	s_lshl_b64 s[14:15], s[12:13], 12
	s_add_i32 s9, s9, s2
	v_add_f32_dpp v36, v36, v36 quad_perm:[1,0,3,2] row_mask:0xf bank_mask:0xf
	v_lshl_add_u64 v[10:11], s[14:15], 0, v[8:9]
	s_nop 0
	v_add_f32_dpp v36, v36, v36 quad_perm:[2,3,0,1] row_mask:0xf bank_mask:0xf
	v_lshl_add_u64 v[10:11], s[14:15], 0, v[8:9]
	s_nop 0
	v_add_f32_dpp v36, v36, v36 row_half_mirror row_mask:0xf bank_mask:0xf
; DI float bflo(unsigned v) { return __uint_as_float(v << 16); }
; DI float bfhi(unsigned v) { return __uint_as_float(v & 0xffff0000u); }
; DI size_t blk(size_t row, int k, int R) { return ((size_t)(k >> 5) * R + row) * 32 + (k & 31); }
; DI void final_norm_phase(const Params& p) {
;     ...
;   for (int t = wv; t < NTOK; t += nw) {
;     const bf16_t* src = p.xb + blk(t, lane * 16, NTOK);
;     const u32x4 a = *(const u32x4*)src, b = *(const u32x4*)(src + 8);
;     float v[16]; float ss = 0.f;
; #pragma unroll
;     for (int e = 0; e < 4; ++e) { v[2 * e] = bflo(a[e]); v[2 * e + 1] = bfhi(a[e]); v[8 + 2 * e] = bflo(b[e]); v[8 + 2 * e + 1] = bfhi(b[e]); }
; #pragma unroll
;     for (int i = 0; i < 16; ++i) ss += v[i] * v[i];
; #pragma unroll
;     for (int d = 1; d < 64; d <<= 1) ss += __shfl_xor(ss, d);
;     const float rs = rsqrtf(ss * (1.f / 1024.f) + 1e-6f);
;     float* row = p.out + (size_t)t * 1024 + lane * 16;
; #pragma unroll
;     for (int i = 0; i < 4; ++i) {
;       const f32x4 gn = *(const f32x4*)(p.final_norm + lane * 16 + 4 * i);
;       f32x4 o; o[0] = v[4 * i] * rs * gn[0]; o[1] = v[4 * i + 1] * rs * gn[1]; o[2] = v[4 * i + 2] * rs * gn[2]; o[3] = v[4 * i + 3] * rs * gn[3];
;       *(f32x4*)(row + 4 * i) = o;
;     }
	v_lshl_add_u64 v[10:11], s[14:15], 0, v[8:9]
	s_nop 0
	v_add_f32_dpp v36, v36, v36 row_mirror row_mask:0xf bank_mask:0xf
	v_lshl_add_u64 v[10:11], s[14:15], 0, v[8:9]
	s_nop 0
	v_readlane_b32 s16, v36, 0
	v_readlane_b32 s17, v36, 16
	v_readlane_b32 s18, v36, 32
	v_readlane_b32 s19, v36, 48
	s_nop 1
	v_mov_b32_e32 v37, s16
	v_add_f32_e32 v37, s17, v37
	v_add_f32_e32 v37, s18, v37
	v_add_f32_e32 v37, s19, v37
	v_fmamk_f32 v37, v37, 0x3a800000, v12
	v_mul_f32_e32 v38, 0x4b800000, v37
	v_cmp_gt_f32_e32 vcc, s3, v37
	s_nop 1
	v_cndmask_b32_e32 v37, v37, v38, vcc
	v_rsq_f32_e32 v37, v37
	s_nop 0
	v_mul_f32_e32 v38, 0x45800000, v37
	v_cndmask_b32_e32 v37, v37, v38, vcc
	v_mul_f32_e32 v20, v20, v37
	v_mul_f32_e32 v21, v21, v37
	v_mul_f32_e32 v22, v22, v37
	v_mul_f32_e32 v23, v23, v37
	v_mul_f32_e32 v24, v24, v37
	v_mul_f32_e32 v25, v25, v37
	v_mul_f32_e32 v26, v26, v37
	v_mul_f32_e32 v27, v27, v37
	v_mul_f32_e32 v28, v28, v37
	v_mul_f32_e32 v29, v29, v37
	v_mul_f32_e32 v30, v30, v37
	v_mul_f32_e32 v31, v31, v37
	v_mul_f32_e32 v32, v32, v37
	v_mul_f32_e32 v33, v33, v37
	v_mul_f32_e32 v34, v34, v37
	v_mul_f32_e32 v35, v35, v37
	v_mul_f32_e32 v20, v20, v50
	v_mul_f32_e32 v21, v21, v51
	v_mul_f32_e32 v22, v22, v52
	v_mul_f32_e32 v23, v23, v53
	v_mul_f32_e32 v24, v24, v54
	v_mul_f32_e32 v25, v25, v55
	v_mul_f32_e32 v26, v26, v56
	v_mul_f32_e32 v27, v27, v57
	v_mul_f32_e32 v28, v28, v58
	v_mul_f32_e32 v29, v29, v59
	v_mul_f32_e32 v30, v30, v60
	v_mul_f32_e32 v31, v31, v61
	v_mul_f32_e32 v32, v32, v62
	v_mul_f32_e32 v33, v33, v63
	v_mul_f32_e32 v34, v34, v64
	v_mul_f32_e32 v35, v35, v65
	global_store_dwordx4 v[10:11], v[20:23], off
	global_store_dwordx4 v[10:11], v[24:27], off offset:16
	global_store_dwordx4 v[10:11], v[28:31], off offset:32
	global_store_dwordx4 v[10:11], v[32:35], off offset:48
	s_cmp_gt_i32 s9, s8
	s_cbranch_scc1 .Lfin_done
	v_lshlrev_b32_e32 v20, 16, v106
	v_and_b32_e32 v21, 0xffff0000, v106
	v_lshlrev_b32_e32 v22, 16, v107
	v_and_b32_e32 v23, 0xffff0000, v107
	v_lshlrev_b32_e32 v24, 16, v108
	v_and_b32_e32 v25, 0xffff0000, v108
	v_lshlrev_b32_e32 v26, 16, v109
	v_and_b32_e32 v27, 0xffff0000, v109
	v_lshlrev_b32_e32 v28, 16, v110
	v_and_b32_e32 v29, 0xffff0000, v110
	v_lshlrev_b32_e32 v30, 16, v111
	v_and_b32_e32 v31, 0xffff0000, v111
	v_lshlrev_b32_e32 v32, 16, v112
	v_and_b32_e32 v33, 0xffff0000, v112
	v_lshlrev_b32_e32 v34, 16, v113
	v_and_b32_e32 v35, 0xffff0000, v113
	v_mul_f32_e32 v36, v20, v20
	v_fmac_f32_e32 v36, v21, v21
	v_fmac_f32_e32 v36, v22, v22
	v_fmac_f32_e32 v36, v23, v23
	v_fmac_f32_e32 v36, v24, v24
	v_fmac_f32_e32 v36, v25, v25
	v_fmac_f32_e32 v36, v26, v26
	v_fmac_f32_e32 v36, v27, v27
	v_fmac_f32_e32 v36, v28, v28
	v_fmac_f32_e32 v36, v29, v29
	v_fmac_f32_e32 v36, v30, v30
	v_fmac_f32_e32 v36, v31, v31
	v_fmac_f32_e32 v36, v32, v32
	v_fmac_f32_e32 v36, v33, v33
	v_fmac_f32_e32 v36, v34, v34
	v_fmac_f32_e32 v36, v35, v35
	s_mov_b32 s12, s9
	s_lshl_b64 s[14:15], s[12:13], 12
	s_add_i32 s9, s9, s2
	v_add_f32_dpp v36, v36, v36 quad_perm:[1,0,3,2] row_mask:0xf bank_mask:0xf
	v_lshl_add_u64 v[10:11], s[14:15], 0, v[8:9]
	s_nop 0
	v_add_f32_dpp v36, v36, v36 quad_perm:[2,3,0,1] row_mask:0xf bank_mask:0xf
	v_lshl_add_u64 v[10:11], s[14:15], 0, v[8:9]
	s_nop 0
	v_add_f32_dpp v36, v36, v36 row_half_mirror row_mask:0xf bank_mask:0xf
	v_lshl_add_u64 v[10:11], s[14:15], 0, v[8:9]
	s_nop 0
	v_add_f32_dpp v36, v36, v36 row_mirror row_mask:0xf bank_mask:0xf
	v_lshl_add_u64 v[10:11], s[14:15], 0, v[8:9]
	s_nop 0
	v_readlane_b32 s16, v36, 0
	v_readlane_b32 s17, v36, 16
	v_readlane_b32 s18, v36, 32
	v_readlane_b32 s19, v36, 48
	s_nop 1
	v_mov_b32_e32 v37, s16
	v_add_f32_e32 v37, s17, v37
	v_add_f32_e32 v37, s18, v37
	v_add_f32_e32 v37, s19, v37
	v_fmamk_f32 v37, v37, 0x3a800000, v12
	v_mul_f32_e32 v38, 0x4b800000, v37
	v_cmp_gt_f32_e32 vcc, s3, v37
	s_nop 1
	v_cndmask_b32_e32 v37, v37, v38, vcc
	v_rsq_f32_e32 v37, v37
	s_nop 0
	v_mul_f32_e32 v38, 0x45800000, v37
	v_cndmask_b32_e32 v37, v37, v38, vcc
	v_mul_f32_e32 v20, v20, v37
	v_mul_f32_e32 v21, v21, v37
	v_mul_f32_e32 v22, v22, v37
	v_mul_f32_e32 v23, v23, v37
	v_mul_f32_e32 v24, v24, v37
	v_mul_f32_e32 v25, v25, v37
	v_mul_f32_e32 v26, v26, v37
	v_mul_f32_e32 v27, v27, v37
	v_mul_f32_e32 v28, v28, v37
	v_mul_f32_e32 v29, v29, v37
	v_mul_f32_e32 v30, v30, v37
	v_mul_f32_e32 v31, v31, v37
	v_mul_f32_e32 v32, v32, v37
	v_mul_f32_e32 v33, v33, v37
	v_mul_f32_e32 v34, v34, v37
	v_mul_f32_e32 v35, v35, v37
	v_mul_f32_e32 v20, v20, v50
	v_mul_f32_e32 v21, v21, v51
	v_mul_f32_e32 v22, v22, v52
	v_mul_f32_e32 v23, v23, v53
	v_mul_f32_e32 v24, v24, v54
	v_mul_f32_e32 v25, v25, v55
	v_mul_f32_e32 v26, v26, v56
	v_mul_f32_e32 v27, v27, v57
	v_mul_f32_e32 v28, v28, v58
	v_mul_f32_e32 v29, v29, v59
	v_mul_f32_e32 v30, v30, v60
	v_mul_f32_e32 v31, v31, v61
	v_mul_f32_e32 v32, v32, v62
	v_mul_f32_e32 v33, v33, v63
	v_mul_f32_e32 v34, v34, v64
	v_mul_f32_e32 v35, v35, v65
	global_store_dwordx4 v[10:11], v[20:23], off
	global_store_dwordx4 v[10:11], v[24:27], off offset:16
	global_store_dwordx4 v[10:11], v[28:31], off offset:32
	global_store_dwordx4 v[10:11], v[32:35], off offset:48
	s_cmp_gt_i32 s9, s8
	s_cbranch_scc1 .Lfin_done
; DI float bflo(unsigned v) { return __uint_as_float(v << 16); }
; DI float bfhi(unsigned v) { return __uint_as_float(v & 0xffff0000u); }
; DI size_t blk(size_t row, int k, int R) { return ((size_t)(k >> 5) * R + row) * 32 + (k & 31); }
; DI void final_norm_phase(const Params& p) {
;     ...
;   for (int t = wv; t < NTOK; t += nw) {
;     const bf16_t* src = p.xb + blk(t, lane * 16, NTOK);
;     const u32x4 a = *(const u32x4*)src, b = *(const u32x4*)(src + 8);
;     float v[16]; float ss = 0.f;
; #pragma unroll
;     for (int e = 0; e < 4; ++e) { v[2 * e] = bflo(a[e]); v[2 * e + 1] = bfhi(a[e]); v[8 + 2 * e] = bflo(b[e]); v[8 + 2 * e + 1] = bfhi(b[e]); }
; #pragma unroll
;     for (int i = 0; i < 16; ++i) ss += v[i] * v[i];
; #pragma unroll
;     for (int d = 1; d < 64; d <<= 1) ss += __shfl_xor(ss, d);
;     const float rs = rsqrtf(ss * (1.f / 1024.f) + 1e-6f);
;     float* row = p.out + (size_t)t * 1024 + lane * 16;
; #pragma unroll
;     for (int i = 0; i < 4; ++i) {
;       const f32x4 gn = *(const f32x4*)(p.final_norm + lane * 16 + 4 * i);
;       f32x4 o; o[0] = v[4 * i] * rs * gn[0]; o[1] = v[4 * i + 1] * rs * gn[1]; o[2] = v[4 * i + 2] * rs * gn[2]; o[3] = v[4 * i + 3] * rs * gn[3];
;       *(f32x4*)(row + 4 * i) = o;
;     }
	v_lshlrev_b32_e32 v20, 16, v114
	v_and_b32_e32 v21, 0xffff0000, v114
	v_lshlrev_b32_e32 v22, 16, v115
	v_and_b32_e32 v23, 0xffff0000, v115
	v_lshlrev_b32_e32 v24, 16, v116
	v_and_b32_e32 v25, 0xffff0000, v116
	v_lshlrev_b32_e32 v26, 16, v117
	v_and_b32_e32 v27, 0xffff0000, v117
	v_lshlrev_b32_e32 v28, 16, v118
	v_and_b32_e32 v29, 0xffff0000, v118
	v_lshlrev_b32_e32 v30, 16, v119
	v_and_b32_e32 v31, 0xffff0000, v119
	v_lshlrev_b32_e32 v32, 16, v120
	v_and_b32_e32 v33, 0xffff0000, v120
	v_lshlrev_b32_e32 v34, 16, v121
	v_and_b32_e32 v35, 0xffff0000, v121
	v_mul_f32_e32 v36, v20, v20
	v_fmac_f32_e32 v36, v21, v21
	v_fmac_f32_e32 v36, v22, v22
	v_fmac_f32_e32 v36, v23, v23
	v_fmac_f32_e32 v36, v24, v24
	v_fmac_f32_e32 v36, v25, v25
	v_fmac_f32_e32 v36, v26, v26
	v_fmac_f32_e32 v36, v27, v27
	v_fmac_f32_e32 v36, v28, v28
	v_fmac_f32_e32 v36, v29, v29
	v_fmac_f32_e32 v36, v30, v30
	v_fmac_f32_e32 v36, v31, v31
	v_fmac_f32_e32 v36, v32, v32
	v_fmac_f32_e32 v36, v33, v33
	v_fmac_f32_e32 v36, v34, v34
	v_fmac_f32_e32 v36, v35, v35
	s_mov_b32 s12, s9
	s_lshl_b64 s[14:15], s[12:13], 12
	s_add_i32 s9, s9, s2
	v_add_f32_dpp v36, v36, v36 quad_perm:[1,0,3,2] row_mask:0xf bank_mask:0xf
	v_lshl_add_u64 v[10:11], s[14:15], 0, v[8:9]
	s_nop 0
	v_add_f32_dpp v36, v36, v36 quad_perm:[2,3,0,1] row_mask:0xf bank_mask:0xf
	v_lshl_add_u64 v[10:11], s[14:15], 0, v[8:9]
	s_nop 0
	v_add_f32_dpp v36, v36, v36 row_half_mirror row_mask:0xf bank_mask:0xf
	v_lshl_add_u64 v[10:11], s[14:15], 0, v[8:9]
	s_nop 0
	v_add_f32_dpp v36, v36, v36 row_mirror row_mask:0xf bank_mask:0xf
	v_lshl_add_u64 v[10:11], s[14:15], 0, v[8:9]
	s_nop 0
	v_readlane_b32 s16, v36, 0
	v_readlane_b32 s17, v36, 16
	v_readlane_b32 s18, v36, 32
	v_readlane_b32 s19, v36, 48
	s_nop 1
	v_mov_b32_e32 v37, s16
	v_add_f32_e32 v37, s17, v37
	v_add_f32_e32 v37, s18, v37
	v_add_f32_e32 v37, s19, v37
	v_fmamk_f32 v37, v37, 0x3a800000, v12
	v_mul_f32_e32 v38, 0x4b800000, v37
	v_cmp_gt_f32_e32 vcc, s3, v37
	s_nop 1
	v_cndmask_b32_e32 v37, v37, v38, vcc
	v_rsq_f32_e32 v37, v37
	s_nop 0
	v_mul_f32_e32 v38, 0x45800000, v37
	v_cndmask_b32_e32 v37, v37, v38, vcc
	v_mul_f32_e32 v20, v20, v37
	v_mul_f32_e32 v21, v21, v37
	v_mul_f32_e32 v22, v22, v37
	v_mul_f32_e32 v23, v23, v37
	v_mul_f32_e32 v24, v24, v37
	v_mul_f32_e32 v25, v25, v37
	v_mul_f32_e32 v26, v26, v37
	v_mul_f32_e32 v27, v27, v37
	v_mul_f32_e32 v28, v28, v37
	v_mul_f32_e32 v29, v29, v37
	v_mul_f32_e32 v30, v30, v37
	v_mul_f32_e32 v31, v31, v37
	v_mul_f32_e32 v32, v32, v37
	v_mul_f32_e32 v33, v33, v37
	v_mul_f32_e32 v34, v34, v37
	v_mul_f32_e32 v35, v35, v37
	v_mul_f32_e32 v20, v20, v50
	v_mul_f32_e32 v21, v21, v51
	v_mul_f32_e32 v22, v22, v52
	v_mul_f32_e32 v23, v23, v53
	v_mul_f32_e32 v24, v24, v54
	v_mul_f32_e32 v25, v25, v55
	v_mul_f32_e32 v26, v26, v56
	v_mul_f32_e32 v27, v27, v57
	v_mul_f32_e32 v28, v28, v58
	v_mul_f32_e32 v29, v29, v59
	v_mul_f32_e32 v30, v30, v60
	v_mul_f32_e32 v31, v31, v61
	v_mul_f32_e32 v32, v32, v62
	v_mul_f32_e32 v33, v33, v63
	v_mul_f32_e32 v34, v34, v64
	v_mul_f32_e32 v35, v35, v65
	global_store_dwordx4 v[10:11], v[20:23], off
	global_store_dwordx4 v[10:11], v[24:27], off offset:16
	global_store_dwordx4 v[10:11], v[28:31], off offset:32
	global_store_dwordx4 v[10:11], v[32:35], off offset:48
	s_cmp_gt_i32 s9, s8
	s_cbranch_scc1 .Lfin_done
; DI float bflo(unsigned v) { return __uint_as_float(v << 16); }
; DI float bfhi(unsigned v) { return __uint_as_float(v & 0xffff0000u); }
; DI size_t blk(size_t row, int k, int R) { return ((size_t)(k >> 5) * R + row) * 32 + (k & 31); }
; DI void final_norm_phase(const Params& p) {
;     ...
;   for (int t = wv; t < NTOK; t += nw) {
;     const bf16_t* src = p.xb + blk(t, lane * 16, NTOK);
;     const u32x4 a = *(const u32x4*)src, b = *(const u32x4*)(src + 8);
;     float v[16]; float ss = 0.f;
; #pragma unroll
;     for (int e = 0; e < 4; ++e) { v[2 * e] = bflo(a[e]); v[2 * e + 1] = bfhi(a[e]); v[8 + 2 * e] = bflo(b[e]); v[8 + 2 * e + 1] = bfhi(b[e]); }
; #pragma unroll
;     for (int i = 0; i < 16; ++i) ss += v[i] * v[i];
; #pragma unroll
;     for (int d = 1; d < 64; d <<= 1) ss += __shfl_xor(ss, d);
;     const float rs = rsqrtf(ss * (1.f / 1024.f) + 1e-6f);
;     float* row = p.out + (size_t)t * 1024 + lane * 16;
; #pragma unroll
;     for (int i = 0; i < 4; ++i) {
;       const f32x4 gn = *(const f32x4*)(p.final_norm + lane * 16 + 4 * i);
;       f32x4 o; o[0] = v[4 * i] * rs * gn[0]; o[1] = v[4 * i + 1] * rs * gn[1]; o[2] = v[4 * i + 2] * rs * gn[2]; o[3] = v[4 * i + 3] * rs * gn[3];
;       *(f32x4*)(row + 4 * i) = o;
;     }
	v_lshlrev_b32_e32 v20, 16, v122
	v_and_b32_e32 v21, 0xffff0000, v122
	v_lshlrev_b32_e32 v22, 16, v123
	v_and_b32_e32 v23, 0xffff0000, v123
	v_lshlrev_b32_e32 v24, 16, v124
	v_and_b32_e32 v25, 0xffff0000, v124
	v_lshlrev_b32_e32 v26, 16, v125
	v_and_b32_e32 v27, 0xffff0000, v125
	v_lshlrev_b32_e32 v28, 16, v126
	v_and_b32_e32 v29, 0xffff0000, v126
	v_lshlrev_b32_e32 v30, 16, v127
	v_and_b32_e32 v31, 0xffff0000, v127
	v_lshlrev_b32_e32 v32, 16, v128
	v_and_b32_e32 v33, 0xffff0000, v128
	v_lshlrev_b32_e32 v34, 16, v129
	v_and_b32_e32 v35, 0xffff0000, v129
	v_mul_f32_e32 v36, v20, v20
	v_fmac_f32_e32 v36, v21, v21
	v_fmac_f32_e32 v36, v22, v22
	v_fmac_f32_e32 v36, v23, v23
	v_fmac_f32_e32 v36, v24, v24
	v_fmac_f32_e32 v36, v25, v25
	v_fmac_f32_e32 v36, v26, v26
	v_fmac_f32_e32 v36, v27, v27
	v_fmac_f32_e32 v36, v28, v28
	v_fmac_f32_e32 v36, v29, v29
	v_fmac_f32_e32 v36, v30, v30
	v_fmac_f32_e32 v36, v31, v31
	v_fmac_f32_e32 v36, v32, v32
	v_fmac_f32_e32 v36, v33, v33
	v_fmac_f32_e32 v36, v34, v34
	v_fmac_f32_e32 v36, v35, v35
	s_mov_b32 s12, s9
	s_lshl_b64 s[14:15], s[12:13], 12
	s_add_i32 s9, s9, s2
	v_add_f32_dpp v36, v36, v36 quad_perm:[1,0,3,2] row_mask:0xf bank_mask:0xf
	v_lshl_add_u64 v[10:11], s[14:15], 0, v[8:9]
	s_nop 0
	v_add_f32_dpp v36, v36, v36 quad_perm:[2,3,0,1] row_mask:0xf bank_mask:0xf
	v_lshl_add_u64 v[10:11], s[14:15], 0, v[8:9]
	s_nop 0
	v_add_f32_dpp v36, v36, v36 row_half_mirror row_mask:0xf bank_mask:0xf
	v_lshl_add_u64 v[10:11], s[14:15], 0, v[8:9]
	s_nop 0
	v_add_f32_dpp v36, v36, v36 row_mirror row_mask:0xf bank_mask:0xf
	v_lshl_add_u64 v[10:11], s[14:15], 0, v[8:9]
	s_nop 0
	v_readlane_b32 s16, v36, 0
	v_readlane_b32 s17, v36, 16
	v_readlane_b32 s18, v36, 32
	v_readlane_b32 s19, v36, 48
	s_nop 1
	v_mov_b32_e32 v37, s16
	v_add_f32_e32 v37, s17, v37
	v_add_f32_e32 v37, s18, v37
	v_add_f32_e32 v37, s19, v37
	v_fmamk_f32 v37, v37, 0x3a800000, v12
	v_mul_f32_e32 v38, 0x4b800000, v37
	v_cmp_gt_f32_e32 vcc, s3, v37
	s_nop 1
	v_cndmask_b32_e32 v37, v37, v38, vcc
	v_rsq_f32_e32 v37, v37
	s_nop 0
	v_mul_f32_e32 v38, 0x45800000, v37
	v_cndmask_b32_e32 v37, v37, v38, vcc
	v_mul_f32_e32 v20, v20, v37
	v_mul_f32_e32 v21, v21, v37
	v_mul_f32_e32 v22, v22, v37
	v_mul_f32_e32 v23, v23, v37
	v_mul_f32_e32 v24, v24, v37
	v_mul_f32_e32 v25, v25, v37
	v_mul_f32_e32 v26, v26, v37
	v_mul_f32_e32 v27, v27, v37
	v_mul_f32_e32 v28, v28, v37
	v_mul_f32_e32 v29, v29, v37
	v_mul_f32_e32 v30, v30, v37
	v_mul_f32_e32 v31, v31, v37
	v_mul_f32_e32 v32, v32, v37
	v_mul_f32_e32 v33, v33, v37
	v_mul_f32_e32 v34, v34, v37
	v_mul_f32_e32 v35, v35, v37
	v_mul_f32_e32 v20, v20, v50
	v_mul_f32_e32 v21, v21, v51
	v_mul_f32_e32 v22, v22, v52
	v_mul_f32_e32 v23, v23, v53
	v_mul_f32_e32 v24, v24, v54
	v_mul_f32_e32 v25, v25, v55
	v_mul_f32_e32 v26, v26, v56
	v_mul_f32_e32 v27, v27, v57
	v_mul_f32_e32 v28, v28, v58
	v_mul_f32_e32 v29, v29, v59
	v_mul_f32_e32 v30, v30, v60
	v_mul_f32_e32 v31, v31, v61
	v_mul_f32_e32 v32, v32, v62
	v_mul_f32_e32 v33, v33, v63
	v_mul_f32_e32 v34, v34, v64
	v_mul_f32_e32 v35, v35, v65
	global_store_dwordx4 v[10:11], v[20:23], off
	global_store_dwordx4 v[10:11], v[24:27], off offset:16
	global_store_dwordx4 v[10:11], v[28:31], off offset:32
	global_store_dwordx4 v[10:11], v[32:35], off offset:48
	s_min_i32 s12, s20, s8
	s_lshl_b64 s[14:15], s[12:13], 6
	s_add_i32 s20, s20, s2
	v_lshl_add_u64 v[10:11], s[14:15], 0, v[4:5]
	global_load_dwordx4 v[98:101], v[10:11], off
	global_load_dwordx4 v[102:105], v[10:11], off offset:16
	s_min_i32 s12, s20, s8
	s_lshl_b64 s[14:15], s[12:13], 6
	s_add_i32 s20, s20, s2
	v_lshl_add_u64 v[10:11], s[14:15], 0, v[4:5]
	global_load_dwordx4 v[106:109], v[10:11], off
	global_load_dwordx4 v[110:113], v[10:11], off offset:16
	s_min_i32 s12, s20, s8
	s_lshl_b64 s[14:15], s[12:13], 6
	s_add_i32 s20, s20, s2
	v_lshl_add_u64 v[10:11], s[14:15], 0, v[4:5]
	global_load_dwordx4 v[114:117], v[10:11], off
	global_load_dwordx4 v[118:121], v[10:11], off offset:16
	s_min_i32 s12, s20, s8
	s_lshl_b64 s[14:15], s[12:13], 6
	s_add_i32 s20, s20, s2
	v_lshl_add_u64 v[10:11], s[14:15], 0, v[4:5]
	global_load_dwordx4 v[122:125], v[10:11], off
	global_load_dwordx4 v[126:129], v[10:11], off offset:16
	s_waitcnt vmcnt(24)
	s_branch .Lfin_loop
.Lfin_done:
.LBB0_1058:
	s_endpgm
